# GEMM K-loops: priority kept raised through the closing barrier of each compute phase (s_setprio 0 after the barrier instead of before), on top of raising it before the opening barrier
# speedup vs baseline: 1.0050x; 1.0031x over previous
; #define PG8_STAGE(bufoff, gbase, voff) do { _Pragma("unroll") for (int _i = 0; _i < 2; ++_i) \
;         __builtin_amdgcn_global_load_lds((const unsigned*)((const char*)(gbase) + (voff)[_i]), (PG8_LAS unsigned*)(lds + (bufoff) + ldsw + _i * 8192), 16, 0, 0); } while (0)
; #define PG8_LDA(dst, b, h) do { _Pragma("unroll") for (int m = 0; m < 4; ++m) _Pragma("unroll") for (int k = 0; k < 2; ++k) dst[m][k] = *(const PG8_LAS bf16x8*)(lds + PG8_SA(b, h) + aoff + m * 2048 + k * 1024); } while (0)
; #define PG8_LDB(dst, b, h) do { _Pragma("unroll") for (int n = 0; n < 2; ++n) _Pragma("unroll") for (int k = 0; k < 2; ++k) dst[n][k] = *(const PG8_LAS bf16x8*)(lds + PG8_SB(b, h) + boff + n * 2048 + k * 1024); } while (0)
; #define PG8_MMA(ai, bj, At, Bt) do { __builtin_amdgcn_s_setprio(1); _Pragma("unroll") for (int m = 0; m < 4; ++m) _Pragma("unroll") for (int n = 0; n < 2; ++n) _Pragma("unroll") for (int k = 0; k < 2; ++k) \
;         acc[ai][bj][m][n] = __builtin_amdgcn_mfma_f32_16x16x32_bf16(Bt[n][k], At[m][k], acc[ai][bj][m][n], 0, 0, 0); __builtin_amdgcn_s_setprio(0); } while (0)
; #define PG8_WAIT_V(n) asm volatile("s_waitcnt vmcnt(" #n ")" ::: "memory")
; #define PG8_WAIT_L(n) asm volatile("s_waitcnt lgkmcnt(" #n ")" ::: "memory")
; template <class Epi, class Sched, bool ALIGN_EPI = false, bool SP2 = false>
; __device__ __forceinline__ void gemm_phase(PG8_LAS unsigned char* lds, const Gemm g, const Sched& S, const Epi& E) {
;     ...
;             const bool last = (t == nt - 2);
;             const char* a1 = cA + (size_t)(t + 1) * kstep;
;             const char* a2 = last ? nA : cA + (size_t)(t + 2) * kstep; const char* b2 = last ? nB : cB + (size_t)(t + 2) * kstep;
;             const char* a3 = a2 + kstep; const char* b3 = b2 + kstep;
;             if (last && has_next) S.a_ready(nxt);
;             if constexpr (SP2) {
;             PG8_LDB(B0, 0, 0); PG8_LDB(B1, 0, 1); PG8_SCHED; PG8_LDA(At, 0, 0); PG8_STAGE(PG8_SA(1, 1), a1 + hstep, voffA);
;             PG8_WAIT_V(8); PG8_WAIT_L(0); PG8_BAR; PG8_MMA(0, 0, At, B0); PG8_MMA(0, 1, At, B1); PG8_BAR; PG8_SCHED;
;             PG8_LDA(At, 0, 1); PG8_STAGE(PG8_SB(0, 0), b2, voffB); PG8_STAGE(PG8_SB(0, 1), b2 + hstep, voffB); PG8_STAGE(PG8_SA(0, 0), a2, voffA);
;             PG8_WAIT_V(8); PG8_WAIT_L(0); PG8_BAR; PG8_MMA(1, 0, At, B0); PG8_MMA(1, 1, At, B1); PG8_BAR; PG8_SCHED;
.LBB0_66:
	s_add_u32 s34, s4, 0xfff80080
	s_addc_u32 s35, s5, -1
	s_add_i32 s95, 0, 0x10000
	s_cmp_eq_u32 s94, 28
	s_cselect_b32 s67, s49, s35
	s_cselect_b32 s66, s90, s34
	v_add_u32_e32 v142, s95, v148
	s_cselect_b32 s63, s43, s93
	s_cselect_b32 s62, s91, s92
	s_add_i32 s34, 0, 0x14000
	ds_read_b128 v[138:141], v142
	ds_read_b128 v[150:153], v142 offset:1024
	ds_read_b128 v[154:157], v142 offset:2048
	ds_read_b128 v[158:161], v142 offset:3072
	v_add_u32_e32 v142, s34, v148
	ds_read_b128 v[162:165], v142
	ds_read_b128 v[166:169], v142 offset:1024
	ds_read_b128 v[170:173], v142 offset:2048
	ds_read_b128 v[174:177], v142 offset:3072
	v_lshl_add_u64 v[142:143], s[4:5], 0, v[134:135]
	s_add_i32 m0, s80, 0xc000
	ds_read_b128 v[178:181], v149
	ds_read_b128 v[182:185], v149 offset:1024
	ds_read_b128 v[186:189], v149 offset:2048
	ds_read_b128 v[190:193], v149 offset:3072
	ds_read_b128 v[194:197], v149 offset:4096
	ds_read_b128 v[198:201], v149 offset:5120
	ds_read_b128 v[210:213], v149 offset:6144
	ds_read_b128 v[214:217], v149 offset:7168
	global_load_lds_dwordx4 v[142:143], off
	v_lshl_add_u64 v[142:143], s[4:5], 0, v[136:137]
	s_add_i32 m0, s80, 0xe000
	s_nop 0
	global_load_lds_dwordx4 v[142:143], off
	s_waitcnt vmcnt(8)
	s_waitcnt lgkmcnt(0)
	s_setprio 1
	s_barrier
	s_waitcnt lgkmcnt(0)
	v_mfma_f32_16x16x32_bf16 v[124:127], v[138:141], v[178:181], v[124:127]
	v_mfma_f32_16x16x32_bf16 v[120:123], v[154:157], v[178:181], v[120:123]
	v_mfma_f32_16x16x32_bf16 v[108:111], v[138:141], v[186:189], v[108:111]
	v_mfma_f32_16x16x32_bf16 v[104:107], v[154:157], v[186:189], v[104:107]
	v_mfma_f32_16x16x32_bf16 v[92:95], v[138:141], v[194:197], v[92:95]
	v_mfma_f32_16x16x32_bf16 v[88:91], v[154:157], v[194:197], v[88:91]
	v_mfma_f32_16x16x32_bf16 v[76:79], v[138:141], v[210:213], v[76:79]
	v_mfma_f32_16x16x32_bf16 v[72:75], v[154:157], v[210:213], v[72:75]
	v_mfma_f32_16x16x32_bf16 v[124:127], v[150:153], v[182:185], v[124:127]
	v_mfma_f32_16x16x32_bf16 v[120:123], v[158:161], v[182:185], v[120:123]
	v_mfma_f32_16x16x32_bf16 v[108:111], v[150:153], v[190:193], v[108:111]
	v_mfma_f32_16x16x32_bf16 v[104:107], v[158:161], v[190:193], v[104:107]
	v_mfma_f32_16x16x32_bf16 v[92:95], v[150:153], v[198:201], v[92:95]
	v_mfma_f32_16x16x32_bf16 v[88:91], v[158:161], v[198:201], v[88:91]
	v_mfma_f32_16x16x32_bf16 v[76:79], v[150:153], v[214:217], v[76:79]
	v_mfma_f32_16x16x32_bf16 v[72:75], v[158:161], v[214:217], v[72:75]
	s_setprio 0
	s_setprio 1
	v_mfma_f32_16x16x32_bf16 v[116:119], v[162:165], v[178:181], v[116:119]
	v_mfma_f32_16x16x32_bf16 v[112:115], v[170:173], v[178:181], v[112:115]
	v_mfma_f32_16x16x32_bf16 v[100:103], v[162:165], v[186:189], v[100:103]
	v_mfma_f32_16x16x32_bf16 v[96:99], v[170:173], v[186:189], v[96:99]
	v_mfma_f32_16x16x32_bf16 v[84:87], v[162:165], v[194:197], v[84:87]
	v_mfma_f32_16x16x32_bf16 v[80:83], v[170:173], v[194:197], v[80:83]
	v_mfma_f32_16x16x32_bf16 v[68:71], v[162:165], v[210:213], v[68:71]
	v_mfma_f32_16x16x32_bf16 v[64:67], v[170:173], v[210:213], v[64:67]
	v_mfma_f32_16x16x32_bf16 v[116:119], v[166:169], v[182:185], v[116:119]
	v_mfma_f32_16x16x32_bf16 v[112:115], v[174:177], v[182:185], v[112:115]
	v_mfma_f32_16x16x32_bf16 v[100:103], v[166:169], v[190:193], v[100:103]
	v_mfma_f32_16x16x32_bf16 v[96:99], v[174:177], v[190:193], v[96:99]
	v_mfma_f32_16x16x32_bf16 v[84:87], v[166:169], v[198:201], v[84:87]
	v_mfma_f32_16x16x32_bf16 v[80:83], v[174:177], v[198:201], v[80:83]
	v_mfma_f32_16x16x32_bf16 v[68:71], v[166:169], v[214:217], v[68:71]
	v_mfma_f32_16x16x32_bf16 v[64:67], v[174:177], v[214:217], v[64:67]
	s_barrier
	s_setprio 0
	s_add_i32 s35, s95, s79
	v_lshl_add_u64 v[142:143], s[62:63], 0, v[204:205]
	s_mov_b32 m0, s35
	ds_read_b128 v[178:181], v149 offset:16384
	ds_read_b128 v[182:185], v149 offset:17408
	ds_read_b128 v[186:189], v149 offset:18432
	ds_read_b128 v[190:193], v149 offset:19456
	ds_read_b128 v[194:197], v149 offset:20480
	ds_read_b128 v[198:201], v149 offset:21504
	ds_read_b128 v[210:213], v149 offset:22528
	ds_read_b128 v[214:217], v149 offset:23552
	global_load_lds_dwordx4 v[142:143], off
	s_add_i32 m0, s35, 0x2000
	s_add_u32 s96, s62, 0x80000
	v_lshl_add_u64 v[202:203], s[62:63], 0, v[128:129]
	s_addc_u32 s97, s63, 0
	s_add_i32 s34, s34, s79
	global_load_lds_dwordx4 v[202:203], off
	v_lshl_add_u64 v[206:207], s[96:97], 0, v[204:205]
	s_mov_b32 m0, s34
	v_lshl_add_u64 v[208:209], s[66:67], 0, v[130:131]
	global_load_lds_dwordx4 v[206:207], off
	v_lshl_add_u64 v[206:207], s[96:97], 0, v[128:129]
	s_add_i32 m0, s34, 0x2000
	s_nop 0
	global_load_lds_dwordx4 v[206:207], off
	v_lshl_add_u64 v[206:207], s[66:67], 0, v[132:133]
	s_mov_b32 m0, s80
	s_nop 0
	global_load_lds_dwordx4 v[206:207], off
	s_mov_b32 m0, s81
	s_nop 0
	global_load_lds_dwordx4 v[208:209], off
	s_waitcnt vmcnt(8)
	s_waitcnt lgkmcnt(0)
	s_setprio 1
	s_barrier
; #define PG8_STAGE(bufoff, gbase, voff) do { _Pragma("unroll") for (int _i = 0; _i < 2; ++_i) \
;         __builtin_amdgcn_global_load_lds((const unsigned*)((const char*)(gbase) + (voff)[_i]), (PG8_LAS unsigned*)(lds + (bufoff) + ldsw + _i * 8192), 16, 0, 0); } while (0)
; #define PG8_LDA(dst, b, h) do { _Pragma("unroll") for (int m = 0; m < 4; ++m) _Pragma("unroll") for (int k = 0; k < 2; ++k) dst[m][k] = *(const PG8_LAS bf16x8*)(lds + PG8_SA(b, h) + aoff + m * 2048 + k * 1024); } while (0)
; #define PG8_LDB(dst, b, h) do { _Pragma("unroll") for (int n = 0; n < 2; ++n) _Pragma("unroll") for (int k = 0; k < 2; ++k) dst[n][k] = *(const PG8_LAS bf16x8*)(lds + PG8_SB(b, h) + boff + n * 2048 + k * 1024); } while (0)
; #define PG8_MMA(ai, bj, At, Bt) do { __builtin_amdgcn_s_setprio(1); _Pragma("unroll") for (int m = 0; m < 4; ++m) _Pragma("unroll") for (int n = 0; n < 2; ++n) _Pragma("unroll") for (int k = 0; k < 2; ++k) \
;         acc[ai][bj][m][n] = __builtin_amdgcn_mfma_f32_16x16x32_bf16(Bt[n][k], At[m][k], acc[ai][bj][m][n], 0, 0, 0); __builtin_amdgcn_s_setprio(0); } while (0)
; #define PG8_WAIT_V(n) asm volatile("s_waitcnt vmcnt(" #n ")" ::: "memory")
; #define PG8_WAIT_L(n) asm volatile("s_waitcnt lgkmcnt(" #n ")" ::: "memory")
; #define PG8_BAR __builtin_amdgcn_s_barrier()
; #define PG8_SCHED __builtin_amdgcn_sched_barrier(0)
; template <class Epi, class Sched, bool ALIGN_EPI = false, bool SP2 = false>
; __device__ __forceinline__ void gemm_phase(PG8_LAS unsigned char* lds, const Gemm g, const Sched& S, const Epi& E) {
;     ...
;             PG8_WAIT_V(8); PG8_WAIT_L(0); PG8_BAR; PG8_MMA(1, 0, At, B0); PG8_MMA(1, 1, At, B1); PG8_BAR; PG8_SCHED;
;             PG8_LDB(B0, 1, 0); PG8_LDB(B1, 1, 1); PG8_SCHED; PG8_LDA(At, 1, 0); PG8_STAGE(PG8_SA(0, 1), a2 + hstep, voffA);
;             PG8_WAIT_V(8); PG8_WAIT_L(0); PG8_BAR; PG8_MMA(0, 0, At, B0); PG8_MMA(0, 1, At, B1); PG8_BAR; PG8_SCHED;
	s_waitcnt lgkmcnt(0)
	v_mfma_f32_16x16x32_bf16 v[60:63], v[138:141], v[178:181], v[60:63]
	v_mfma_f32_16x16x32_bf16 v[56:59], v[154:157], v[178:181], v[56:59]
	v_mfma_f32_16x16x32_bf16 v[44:47], v[138:141], v[186:189], v[44:47]
	v_mfma_f32_16x16x32_bf16 v[40:43], v[154:157], v[186:189], v[40:43]
	v_mfma_f32_16x16x32_bf16 v[28:31], v[138:141], v[194:197], v[28:31]
	v_mfma_f32_16x16x32_bf16 v[24:27], v[154:157], v[194:197], v[24:27]
	v_mfma_f32_16x16x32_bf16 v[12:15], v[138:141], v[210:213], v[12:15]
	v_mfma_f32_16x16x32_bf16 v[8:11], v[154:157], v[210:213], v[8:11]
	v_mfma_f32_16x16x32_bf16 v[60:63], v[150:153], v[182:185], v[60:63]
	v_mfma_f32_16x16x32_bf16 v[56:59], v[158:161], v[182:185], v[56:59]
	v_mfma_f32_16x16x32_bf16 v[44:47], v[150:153], v[190:193], v[44:47]
	v_mfma_f32_16x16x32_bf16 v[40:43], v[158:161], v[190:193], v[40:43]
	v_mfma_f32_16x16x32_bf16 v[28:31], v[150:153], v[198:201], v[28:31]
	v_mfma_f32_16x16x32_bf16 v[24:27], v[158:161], v[198:201], v[24:27]
	v_mfma_f32_16x16x32_bf16 v[12:15], v[150:153], v[214:217], v[12:15]
	v_mfma_f32_16x16x32_bf16 v[8:11], v[158:161], v[214:217], v[8:11]
	s_setprio 0
	s_setprio 1
	v_mfma_f32_16x16x32_bf16 v[52:55], v[162:165], v[178:181], v[52:55]
	v_mfma_f32_16x16x32_bf16 v[48:51], v[170:173], v[178:181], v[48:51]
	v_mfma_f32_16x16x32_bf16 v[36:39], v[162:165], v[186:189], v[36:39]
	v_mfma_f32_16x16x32_bf16 v[32:35], v[170:173], v[186:189], v[32:35]
	v_mfma_f32_16x16x32_bf16 v[20:23], v[162:165], v[194:197], v[20:23]
	v_mfma_f32_16x16x32_bf16 v[16:19], v[170:173], v[194:197], v[16:19]
	v_mfma_f32_16x16x32_bf16 v[4:7], v[162:165], v[210:213], v[4:7]
	v_mfma_f32_16x16x32_bf16 v[0:3], v[170:173], v[210:213], v[0:3]
	v_mfma_f32_16x16x32_bf16 v[52:55], v[166:169], v[182:185], v[52:55]
	v_mfma_f32_16x16x32_bf16 v[48:51], v[174:177], v[182:185], v[48:51]
	v_mfma_f32_16x16x32_bf16 v[36:39], v[166:169], v[190:193], v[36:39]
	v_mfma_f32_16x16x32_bf16 v[32:35], v[174:177], v[190:193], v[32:35]
	v_mfma_f32_16x16x32_bf16 v[20:23], v[166:169], v[198:201], v[20:23]
	v_mfma_f32_16x16x32_bf16 v[16:19], v[174:177], v[198:201], v[16:19]
	v_mfma_f32_16x16x32_bf16 v[4:7], v[166:169], v[214:217], v[4:7]
	v_mfma_f32_16x16x32_bf16 v[0:3], v[174:177], v[214:217], v[0:3]
	s_barrier
	s_setprio 0
	s_add_i32 s34, 0, 0x18000
	v_add_u32_e32 v144, s34, v148
	s_add_i32 s35, 0, 0x1c000
	ds_read_b128 v[138:141], v144
	ds_read_b128 v[150:153], v144 offset:1024
	ds_read_b128 v[154:157], v144 offset:2048
	ds_read_b128 v[158:161], v144 offset:3072
	v_add_u32_e32 v144, s35, v148
	ds_read_b128 v[162:165], v144
	ds_read_b128 v[166:169], v144 offset:1024
	ds_read_b128 v[170:173], v144 offset:2048
	ds_read_b128 v[174:177], v144 offset:3072
	s_add_u32 s66, s66, 0x80000
	s_addc_u32 s67, s67, 0
	s_mov_b32 m0, s82
	v_lshl_add_u64 v[218:219], s[66:67], 0, v[132:133]
	ds_read_b128 v[178:181], v149 offset:32768
	ds_read_b128 v[182:185], v149 offset:33792
	ds_read_b128 v[186:189], v149 offset:34816
	ds_read_b128 v[190:193], v149 offset:35840
	ds_read_b128 v[194:197], v149 offset:36864
	ds_read_b128 v[198:201], v149 offset:37888
	ds_read_b128 v[210:213], v149 offset:38912
	ds_read_b128 v[214:217], v149 offset:39936
	global_load_lds_dwordx4 v[218:219], off
	v_lshl_add_u64 v[218:219], s[66:67], 0, v[130:131]
	s_mov_b32 m0, s83
	s_nop 0
	global_load_lds_dwordx4 v[218:219], off
	s_waitcnt vmcnt(8)
	s_waitcnt lgkmcnt(0)
	s_setprio 1
	s_barrier
	s_waitcnt lgkmcnt(0)
	v_mfma_f32_16x16x32_bf16 v[124:127], v[138:141], v[178:181], v[124:127]
	v_mfma_f32_16x16x32_bf16 v[120:123], v[154:157], v[178:181], v[120:123]
	v_mfma_f32_16x16x32_bf16 v[108:111], v[138:141], v[186:189], v[108:111]
	v_mfma_f32_16x16x32_bf16 v[104:107], v[154:157], v[186:189], v[104:107]
	v_mfma_f32_16x16x32_bf16 v[92:95], v[138:141], v[194:197], v[92:95]
	v_mfma_f32_16x16x32_bf16 v[88:91], v[154:157], v[194:197], v[88:91]
	v_mfma_f32_16x16x32_bf16 v[76:79], v[138:141], v[210:213], v[76:79]
	v_mfma_f32_16x16x32_bf16 v[72:75], v[154:157], v[210:213], v[72:75]
	v_mfma_f32_16x16x32_bf16 v[124:127], v[150:153], v[182:185], v[124:127]
	v_mfma_f32_16x16x32_bf16 v[120:123], v[158:161], v[182:185], v[120:123]
	v_mfma_f32_16x16x32_bf16 v[108:111], v[150:153], v[190:193], v[108:111]
	v_mfma_f32_16x16x32_bf16 v[104:107], v[158:161], v[190:193], v[104:107]
	v_mfma_f32_16x16x32_bf16 v[92:95], v[150:153], v[198:201], v[92:95]
	v_mfma_f32_16x16x32_bf16 v[88:91], v[158:161], v[198:201], v[88:91]
	v_mfma_f32_16x16x32_bf16 v[76:79], v[150:153], v[214:217], v[76:79]
	v_mfma_f32_16x16x32_bf16 v[72:75], v[158:161], v[214:217], v[72:75]
	s_setprio 0
	s_setprio 1
	v_mfma_f32_16x16x32_bf16 v[116:119], v[162:165], v[178:181], v[116:119]
	v_mfma_f32_16x16x32_bf16 v[112:115], v[170:173], v[178:181], v[112:115]
	v_mfma_f32_16x16x32_bf16 v[100:103], v[162:165], v[186:189], v[100:103]
	v_mfma_f32_16x16x32_bf16 v[96:99], v[170:173], v[186:189], v[96:99]
	v_mfma_f32_16x16x32_bf16 v[84:87], v[162:165], v[194:197], v[84:87]
	v_mfma_f32_16x16x32_bf16 v[80:83], v[170:173], v[194:197], v[80:83]
	v_mfma_f32_16x16x32_bf16 v[68:71], v[162:165], v[210:213], v[68:71]
	v_mfma_f32_16x16x32_bf16 v[64:67], v[170:173], v[210:213], v[64:67]
	v_mfma_f32_16x16x32_bf16 v[116:119], v[166:169], v[182:185], v[116:119]
	v_mfma_f32_16x16x32_bf16 v[112:115], v[174:177], v[182:185], v[112:115]
	v_mfma_f32_16x16x32_bf16 v[100:103], v[166:169], v[190:193], v[100:103]
	v_mfma_f32_16x16x32_bf16 v[96:99], v[174:177], v[190:193], v[96:99]
	v_mfma_f32_16x16x32_bf16 v[84:87], v[166:169], v[198:201], v[84:87]
	v_mfma_f32_16x16x32_bf16 v[80:83], v[174:177], v[198:201], v[80:83]
	v_mfma_f32_16x16x32_bf16 v[68:71], v[166:169], v[214:217], v[68:71]
	v_mfma_f32_16x16x32_bf16 v[64:67], v[174:177], v[214:217], v[64:67]
	s_barrier
; #define PG8_STAGE(bufoff, gbase, voff) do { _Pragma("unroll") for (int _i = 0; _i < 2; ++_i) \
;         __builtin_amdgcn_global_load_lds((const unsigned*)((const char*)(gbase) + (voff)[_i]), (PG8_LAS unsigned*)(lds + (bufoff) + ldsw + _i * 8192), 16, 0, 0); } while (0)
; #define PG8_LDA(dst, b, h) do { _Pragma("unroll") for (int m = 0; m < 4; ++m) _Pragma("unroll") for (int k = 0; k < 2; ++k) dst[m][k] = *(const PG8_LAS bf16x8*)(lds + PG8_SA(b, h) + aoff + m * 2048 + k * 1024); } while (0)
; #define PG8_MMA(ai, bj, At, Bt) do { __builtin_amdgcn_s_setprio(1); _Pragma("unroll") for (int m = 0; m < 4; ++m) _Pragma("unroll") for (int n = 0; n < 2; ++n) _Pragma("unroll") for (int k = 0; k < 2; ++k) \
;         acc[ai][bj][m][n] = __builtin_amdgcn_mfma_f32_16x16x32_bf16(Bt[n][k], At[m][k], acc[ai][bj][m][n], 0, 0, 0); __builtin_amdgcn_s_setprio(0); } while (0)
; #define PG8_WAIT_V(n) asm volatile("s_waitcnt vmcnt(" #n ")" ::: "memory")
; #define PG8_WAIT_L(n) asm volatile("s_waitcnt lgkmcnt(" #n ")" ::: "memory")
; #define PG8_BAR __builtin_amdgcn_s_barrier()
; #define PG8_SCHED __builtin_amdgcn_sched_barrier(0)
; template <class Epi, class Sched, bool ALIGN_EPI = false, bool SP2 = false>
; __device__ __forceinline__ void gemm_phase(PG8_LAS unsigned char* lds, const Gemm g, const Sched& S, const Epi& E) {
;     ...
;         for (int t = 0; t < nt; t += 2) {
;     ...
;             PG8_LDA(At, 1, 1); PG8_STAGE(PG8_SB(1, 0), b3, voffB); PG8_STAGE(PG8_SB(1, 1), b3 + hstep, voffB); PG8_STAGE(PG8_SA(1, 0), a3, voffA);
;             PG8_WAIT_V(8); PG8_WAIT_L(0); PG8_BAR; PG8_MMA(1, 0, At, B0); PG8_MMA(1, 1, At, B1); PG8_BAR; PG8_SCHED;
	s_setprio 0
	s_add_i32 s34, s34, s79
	v_lshl_add_u64 v[142:143], v[142:143], 0, s[8:9]
	s_mov_b32 m0, s34
	ds_read_b128 v[178:181], v149 offset:49152
	ds_read_b128 v[182:185], v149 offset:50176
	ds_read_b128 v[186:189], v149 offset:51200
	ds_read_b128 v[190:193], v149 offset:52224
	ds_read_b128 v[194:197], v149 offset:53248
	ds_read_b128 v[198:201], v149 offset:54272
	ds_read_b128 v[210:213], v149 offset:55296
	ds_read_b128 v[214:217], v149 offset:56320
	global_load_lds_dwordx4 v[142:143], off
	s_add_i32 m0, s34, 0x2000
	s_add_u32 s62, s62, 0x80080
	v_lshl_add_u64 v[142:143], v[202:203], 0, s[8:9]
	s_addc_u32 s63, s63, 0
	s_add_i32 s34, s35, s79
	global_load_lds_dwordx4 v[142:143], off
	v_lshl_add_u64 v[142:143], s[62:63], 0, v[204:205]
	s_mov_b32 m0, s34
	s_nop 0
	global_load_lds_dwordx4 v[142:143], off
	v_lshl_add_u64 v[142:143], s[62:63], 0, v[128:129]
	s_add_i32 m0, s34, 0x2000
	s_nop 0
	global_load_lds_dwordx4 v[142:143], off
	v_lshl_add_u64 v[142:143], v[206:207], 0, s[8:9]
	s_mov_b32 m0, s85
	s_nop 0
	global_load_lds_dwordx4 v[142:143], off
	v_lshl_add_u64 v[142:143], v[208:209], 0, s[8:9]
	s_mov_b32 m0, s86
	s_nop 0
	global_load_lds_dwordx4 v[142:143], off
	s_waitcnt vmcnt(8)
	s_waitcnt lgkmcnt(0)
	s_setprio 1
	s_barrier
	s_waitcnt lgkmcnt(0)
	v_mfma_f32_16x16x32_bf16 v[60:63], v[138:141], v[178:181], v[60:63]
	v_mfma_f32_16x16x32_bf16 v[56:59], v[154:157], v[178:181], v[56:59]
	v_mfma_f32_16x16x32_bf16 v[44:47], v[138:141], v[186:189], v[44:47]
	v_mfma_f32_16x16x32_bf16 v[40:43], v[154:157], v[186:189], v[40:43]
	v_mfma_f32_16x16x32_bf16 v[28:31], v[138:141], v[194:197], v[28:31]
	v_mfma_f32_16x16x32_bf16 v[24:27], v[154:157], v[194:197], v[24:27]
	v_mfma_f32_16x16x32_bf16 v[12:15], v[138:141], v[210:213], v[12:15]
	v_mfma_f32_16x16x32_bf16 v[8:11], v[154:157], v[210:213], v[8:11]
	v_mfma_f32_16x16x32_bf16 v[60:63], v[150:153], v[182:185], v[60:63]
	v_mfma_f32_16x16x32_bf16 v[56:59], v[158:161], v[182:185], v[56:59]
	v_mfma_f32_16x16x32_bf16 v[44:47], v[150:153], v[190:193], v[44:47]
	v_mfma_f32_16x16x32_bf16 v[40:43], v[158:161], v[190:193], v[40:43]
	v_mfma_f32_16x16x32_bf16 v[28:31], v[150:153], v[198:201], v[28:31]
	v_mfma_f32_16x16x32_bf16 v[24:27], v[158:161], v[198:201], v[24:27]
	v_mfma_f32_16x16x32_bf16 v[12:15], v[150:153], v[214:217], v[12:15]
	v_mfma_f32_16x16x32_bf16 v[8:11], v[158:161], v[214:217], v[8:11]
	s_setprio 0
	s_setprio 1
	v_mfma_f32_16x16x32_bf16 v[52:55], v[162:165], v[178:181], v[52:55]
	v_mfma_f32_16x16x32_bf16 v[48:51], v[170:173], v[178:181], v[48:51]
	v_mfma_f32_16x16x32_bf16 v[36:39], v[162:165], v[186:189], v[36:39]
	v_mfma_f32_16x16x32_bf16 v[32:35], v[170:173], v[186:189], v[32:35]
	v_mfma_f32_16x16x32_bf16 v[20:23], v[162:165], v[194:197], v[20:23]
	v_mfma_f32_16x16x32_bf16 v[16:19], v[170:173], v[194:197], v[16:19]
	v_mfma_f32_16x16x32_bf16 v[4:7], v[162:165], v[210:213], v[4:7]
	v_mfma_f32_16x16x32_bf16 v[0:3], v[170:173], v[210:213], v[0:3]
	v_mfma_f32_16x16x32_bf16 v[52:55], v[166:169], v[182:185], v[52:55]
	v_mfma_f32_16x16x32_bf16 v[48:51], v[174:177], v[182:185], v[48:51]
	v_mfma_f32_16x16x32_bf16 v[36:39], v[166:169], v[190:193], v[36:39]
	v_mfma_f32_16x16x32_bf16 v[32:35], v[174:177], v[190:193], v[32:35]
	v_mfma_f32_16x16x32_bf16 v[20:23], v[166:169], v[198:201], v[20:23]
	v_mfma_f32_16x16x32_bf16 v[16:19], v[174:177], v[198:201], v[16:19]
	v_mfma_f32_16x16x32_bf16 v[4:7], v[166:169], v[214:217], v[4:7]
	v_mfma_f32_16x16x32_bf16 v[0:3], v[174:177], v[214:217], v[0:3]
	s_barrier
	s_setprio 0
	s_add_i32 s94, s94, 2
	s_add_u32 s4, s4, 0x100
	s_addc_u32 s5, s5, 0
	s_add_u32 s92, s92, 0x100
	s_addc_u32 s93, s93, 0
	s_cmp_gt_u32 s94, 29
	s_cbranch_scc0 .LBB0_66
	s_and_b64 vcc, exec, s[18:19]
	s_cbranch_vccz .LBB0_69
	s_barrier

; #define PG8_STAGE(bufoff, gbase, voff) do { _Pragma("unroll") for (int _i = 0; _i < 2; ++_i) \
;         __builtin_amdgcn_global_load_lds((const unsigned*)((const char*)(gbase) + (voff)[_i]), (PG8_LAS unsigned*)(lds + (bufoff) + ldsw + _i * 8192), 16, 0, 0); } while (0)
; #define PG8_LDA(dst, b, h) do { _Pragma("unroll") for (int m = 0; m < 4; ++m) _Pragma("unroll") for (int k = 0; k < 2; ++k) dst[m][k] = *(const PG8_LAS bf16x8*)(lds + PG8_SA(b, h) + aoff + m * 2048 + k * 1024); } while (0)
; #define PG8_LDB(dst, b, h) do { _Pragma("unroll") for (int n = 0; n < 2; ++n) _Pragma("unroll") for (int k = 0; k < 2; ++k) dst[n][k] = *(const PG8_LAS bf16x8*)(lds + PG8_SB(b, h) + boff + n * 2048 + k * 1024); } while (0)
; #define PG8_MMA(ai, bj, At, Bt) do { __builtin_amdgcn_s_setprio(1); _Pragma("unroll") for (int m = 0; m < 4; ++m) _Pragma("unroll") for (int n = 0; n < 2; ++n) _Pragma("unroll") for (int k = 0; k < 2; ++k) \
;         acc[ai][bj][m][n] = __builtin_amdgcn_mfma_f32_16x16x32_bf16(Bt[n][k], At[m][k], acc[ai][bj][m][n], 0, 0, 0); __builtin_amdgcn_s_setprio(0); } while (0)
; #define PG8_WAIT_V(n) asm volatile("s_waitcnt vmcnt(" #n ")" ::: "memory")
; #define PG8_WAIT_L(n) asm volatile("s_waitcnt lgkmcnt(" #n ")" ::: "memory")
; template <class Epi, class Sched, bool ALIGN_EPI = false, bool SP2 = false>
; __device__ __forceinline__ void gemm_phase(PG8_LAS unsigned char* lds, const Gemm g, const Sched& S, const Epi& E) {
;     ...
;             const bool last = (t == nt - 2);
;             const char* a1 = cA + (size_t)(t + 1) * kstep;
;             const char* a2 = last ? nA : cA + (size_t)(t + 2) * kstep; const char* b2 = last ? nB : cB + (size_t)(t + 2) * kstep;
;             const char* a3 = a2 + kstep; const char* b3 = b2 + kstep;
;             if (last && has_next) S.a_ready(nxt);
;             if constexpr (SP2) {
;             PG8_LDB(B0, 0, 0); PG8_LDB(B1, 0, 1); PG8_SCHED; PG8_LDA(At, 0, 0); PG8_STAGE(PG8_SA(1, 1), a1 + hstep, voffA);
;             PG8_WAIT_V(8); PG8_WAIT_L(0); PG8_BAR; PG8_MMA(0, 0, At, B0); PG8_MMA(0, 1, At, B1); PG8_BAR; PG8_SCHED;
;             PG8_LDA(At, 0, 1); PG8_STAGE(PG8_SB(0, 0), b2, voffB); PG8_STAGE(PG8_SB(0, 1), b2 + hstep, voffB); PG8_STAGE(PG8_SA(0, 0), a2, voffA);
;             PG8_WAIT_V(8); PG8_WAIT_L(0); PG8_BAR; PG8_MMA(1, 0, At, B0); PG8_MMA(1, 1, At, B1); PG8_BAR; PG8_SCHED;
.LBB0_311:
	s_add_u32 s34, s6, 0xfff80080
	s_addc_u32 s35, s7, -1
	s_add_i32 s72, 0, 0x10000
	s_cmp_eq_u32 vcc_hi, 28
	s_cselect_b32 s67, s57, s35
	s_cselect_b32 s66, s93, s34
	s_cselect_b32 s63, s95, vcc_lo
	s_cselect_b32 s62, s98, s99
	s_add_i32 s74, 0, 0x14000
	v_add_u32_e32 v76, s72, v240
	v_add_u32_e32 v156, s74, v240
	ds_read_b128 v[64:67], v76
	ds_read_b128 v[68:71], v76 offset:1024
	ds_read_b128 v[72:75], v76 offset:2048
	ds_read_b128 v[76:79], v76 offset:3072
	ds_read_b128 v[144:147], v156
	ds_read_b128 v[148:151], v156 offset:1024
	ds_read_b128 v[152:155], v156 offset:2048
	ds_read_b128 v[156:159], v156 offset:3072
	v_lshl_add_u64 v[192:193], s[6:7], 0, v[216:217]
	s_add_i32 m0, s80, 0xc000
	ds_read_b128 v[160:163], v241
	ds_read_b128 v[164:167], v241 offset:1024
	ds_read_b128 v[168:171], v241 offset:2048
	ds_read_b128 v[172:175], v241 offset:3072
	ds_read_b128 v[176:179], v241 offset:4096
	ds_read_b128 v[180:183], v241 offset:5120
	ds_read_b128 v[184:187], v241 offset:6144
	ds_read_b128 v[188:191], v241 offset:7168
	global_load_lds_dwordx4 v[192:193], off
	v_lshl_add_u64 v[192:193], s[6:7], 0, v[218:219]
	s_add_i32 m0, s80, 0xe000
	s_nop 0
	global_load_lds_dwordx4 v[192:193], off
	s_waitcnt vmcnt(8)
	s_waitcnt lgkmcnt(0)
	s_setprio 1
	s_barrier
	s_waitcnt lgkmcnt(0)
	v_mfma_f32_16x16x32_bf16 v[140:143], v[64:67], v[160:163], v[140:143]
	v_mfma_f32_16x16x32_bf16 v[136:139], v[72:75], v[160:163], v[136:139]
	v_mfma_f32_16x16x32_bf16 v[124:127], v[64:67], v[168:171], v[124:127]
	v_mfma_f32_16x16x32_bf16 v[120:123], v[72:75], v[168:171], v[120:123]
	v_mfma_f32_16x16x32_bf16 v[108:111], v[64:67], v[176:179], v[108:111]
	v_mfma_f32_16x16x32_bf16 v[104:107], v[72:75], v[176:179], v[104:107]
	v_mfma_f32_16x16x32_bf16 v[92:95], v[64:67], v[184:187], v[92:95]
	v_mfma_f32_16x16x32_bf16 v[88:91], v[72:75], v[184:187], v[88:91]
	v_mfma_f32_16x16x32_bf16 v[140:143], v[68:71], v[164:167], v[140:143]
	v_mfma_f32_16x16x32_bf16 v[136:139], v[76:79], v[164:167], v[136:139]
	v_mfma_f32_16x16x32_bf16 v[124:127], v[68:71], v[172:175], v[124:127]
	v_mfma_f32_16x16x32_bf16 v[120:123], v[76:79], v[172:175], v[120:123]
	v_mfma_f32_16x16x32_bf16 v[108:111], v[68:71], v[180:183], v[108:111]
	v_mfma_f32_16x16x32_bf16 v[104:107], v[76:79], v[180:183], v[104:107]
	v_mfma_f32_16x16x32_bf16 v[92:95], v[68:71], v[188:191], v[92:95]
	v_mfma_f32_16x16x32_bf16 v[88:91], v[76:79], v[188:191], v[88:91]
	s_setprio 0
	s_setprio 1
	v_mfma_f32_16x16x32_bf16 v[132:135], v[144:147], v[160:163], v[132:135]
	v_mfma_f32_16x16x32_bf16 v[128:131], v[152:155], v[160:163], v[128:131]
	v_mfma_f32_16x16x32_bf16 v[116:119], v[144:147], v[168:171], v[116:119]
	v_mfma_f32_16x16x32_bf16 v[112:115], v[152:155], v[168:171], v[112:115]
	v_mfma_f32_16x16x32_bf16 v[100:103], v[144:147], v[176:179], v[100:103]
	v_mfma_f32_16x16x32_bf16 v[96:99], v[152:155], v[176:179], v[96:99]
	v_mfma_f32_16x16x32_bf16 v[84:87], v[144:147], v[184:187], v[84:87]
	v_mfma_f32_16x16x32_bf16 v[80:83], v[152:155], v[184:187], v[80:83]
	v_mfma_f32_16x16x32_bf16 v[132:135], v[148:151], v[164:167], v[132:135]
	v_mfma_f32_16x16x32_bf16 v[128:131], v[156:159], v[164:167], v[128:131]
	v_mfma_f32_16x16x32_bf16 v[116:119], v[148:151], v[172:175], v[116:119]
	v_mfma_f32_16x16x32_bf16 v[112:115], v[156:159], v[172:175], v[112:115]
	v_mfma_f32_16x16x32_bf16 v[100:103], v[148:151], v[180:183], v[100:103]
	v_mfma_f32_16x16x32_bf16 v[96:99], v[156:159], v[180:183], v[96:99]
	v_mfma_f32_16x16x32_bf16 v[84:87], v[148:151], v[188:191], v[84:87]
	v_mfma_f32_16x16x32_bf16 v[80:83], v[156:159], v[188:191], v[80:83]
	s_barrier
	s_setprio 0
	s_add_i32 s34, s72, s79
	v_lshl_add_u64 v[192:193], s[62:63], 0, v[204:205]
	s_mov_b32 m0, s34
	ds_read_b128 v[160:163], v241 offset:16384
	ds_read_b128 v[164:167], v241 offset:17408
	ds_read_b128 v[168:171], v241 offset:18432
	ds_read_b128 v[172:175], v241 offset:19456
	ds_read_b128 v[176:179], v241 offset:20480
	ds_read_b128 v[180:183], v241 offset:21504
	ds_read_b128 v[184:187], v241 offset:22528
	ds_read_b128 v[188:191], v241 offset:23552
	global_load_lds_dwordx4 v[192:193], off
	s_add_i32 m0, s34, 0x2000
	s_add_u32 s34, s62, 0x80000
	v_lshl_add_u64 v[194:195], s[62:63], 0, v[210:211]
	s_addc_u32 s35, s63, 0
	s_add_i32 s72, s74, s79
	global_load_lds_dwordx4 v[194:195], off
	v_lshl_add_u64 v[196:197], s[34:35], 0, v[204:205]
	s_mov_b32 m0, s72
	v_lshl_add_u64 v[198:199], s[66:67], 0, v[212:213]
	global_load_lds_dwordx4 v[196:197], off
	v_lshl_add_u64 v[196:197], s[34:35], 0, v[210:211]
	s_add_i32 m0, s72, 0x2000
	s_nop 0
	global_load_lds_dwordx4 v[196:197], off
	v_lshl_add_u64 v[196:197], s[66:67], 0, v[214:215]
	s_mov_b32 m0, s80
	s_nop 0
	global_load_lds_dwordx4 v[196:197], off
	s_mov_b32 m0, s81
	s_nop 0
	global_load_lds_dwordx4 v[198:199], off
	s_waitcnt vmcnt(8)
	s_waitcnt lgkmcnt(0)
	s_setprio 1
	s_barrier
; #define PG8_STAGE(bufoff, gbase, voff) do { _Pragma("unroll") for (int _i = 0; _i < 2; ++_i) \
;         __builtin_amdgcn_global_load_lds((const unsigned*)((const char*)(gbase) + (voff)[_i]), (PG8_LAS unsigned*)(lds + (bufoff) + ldsw + _i * 8192), 16, 0, 0); } while (0)
; #define PG8_LDA(dst, b, h) do { _Pragma("unroll") for (int m = 0; m < 4; ++m) _Pragma("unroll") for (int k = 0; k < 2; ++k) dst[m][k] = *(const PG8_LAS bf16x8*)(lds + PG8_SA(b, h) + aoff + m * 2048 + k * 1024); } while (0)
; #define PG8_LDB(dst, b, h) do { _Pragma("unroll") for (int n = 0; n < 2; ++n) _Pragma("unroll") for (int k = 0; k < 2; ++k) dst[n][k] = *(const PG8_LAS bf16x8*)(lds + PG8_SB(b, h) + boff + n * 2048 + k * 1024); } while (0)
; #define PG8_MMA(ai, bj, At, Bt) do { __builtin_amdgcn_s_setprio(1); _Pragma("unroll") for (int m = 0; m < 4; ++m) _Pragma("unroll") for (int n = 0; n < 2; ++n) _Pragma("unroll") for (int k = 0; k < 2; ++k) \
;         acc[ai][bj][m][n] = __builtin_amdgcn_mfma_f32_16x16x32_bf16(Bt[n][k], At[m][k], acc[ai][bj][m][n], 0, 0, 0); __builtin_amdgcn_s_setprio(0); } while (0)
; #define PG8_WAIT_V(n) asm volatile("s_waitcnt vmcnt(" #n ")" ::: "memory")
; #define PG8_WAIT_L(n) asm volatile("s_waitcnt lgkmcnt(" #n ")" ::: "memory")
; #define PG8_BAR __builtin_amdgcn_s_barrier()
; #define PG8_SCHED __builtin_amdgcn_sched_barrier(0)
; template <class Epi, class Sched, bool ALIGN_EPI = false, bool SP2 = false>
; __device__ __forceinline__ void gemm_phase(PG8_LAS unsigned char* lds, const Gemm g, const Sched& S, const Epi& E) {
;     ...
;             PG8_WAIT_V(8); PG8_WAIT_L(0); PG8_BAR; PG8_MMA(1, 0, At, B0); PG8_MMA(1, 1, At, B1); PG8_BAR; PG8_SCHED;
;             PG8_LDB(B0, 1, 0); PG8_LDB(B1, 1, 1); PG8_SCHED; PG8_LDA(At, 1, 0); PG8_STAGE(PG8_SA(0, 1), a2 + hstep, voffA);
;             PG8_WAIT_V(8); PG8_WAIT_L(0); PG8_BAR; PG8_MMA(0, 0, At, B0); PG8_MMA(0, 1, At, B1); PG8_BAR; PG8_SCHED;
	s_waitcnt lgkmcnt(0)
	v_mfma_f32_16x16x32_bf16 v[60:63], v[64:67], v[160:163], v[60:63]
	v_mfma_f32_16x16x32_bf16 v[56:59], v[72:75], v[160:163], v[56:59]
	v_mfma_f32_16x16x32_bf16 v[44:47], v[64:67], v[168:171], v[44:47]
	v_mfma_f32_16x16x32_bf16 v[40:43], v[72:75], v[168:171], v[40:43]
	v_mfma_f32_16x16x32_bf16 v[28:31], v[64:67], v[176:179], v[28:31]
	v_mfma_f32_16x16x32_bf16 v[24:27], v[72:75], v[176:179], v[24:27]
	v_mfma_f32_16x16x32_bf16 v[12:15], v[64:67], v[184:187], v[12:15]
	v_mfma_f32_16x16x32_bf16 v[8:11], v[72:75], v[184:187], v[8:11]
	v_mfma_f32_16x16x32_bf16 v[60:63], v[68:71], v[164:167], v[60:63]
	v_mfma_f32_16x16x32_bf16 v[56:59], v[76:79], v[164:167], v[56:59]
	v_mfma_f32_16x16x32_bf16 v[44:47], v[68:71], v[172:175], v[44:47]
	v_mfma_f32_16x16x32_bf16 v[40:43], v[76:79], v[172:175], v[40:43]
	v_mfma_f32_16x16x32_bf16 v[28:31], v[68:71], v[180:183], v[28:31]
	v_mfma_f32_16x16x32_bf16 v[24:27], v[76:79], v[180:183], v[24:27]
	v_mfma_f32_16x16x32_bf16 v[12:15], v[68:71], v[188:191], v[12:15]
	v_mfma_f32_16x16x32_bf16 v[8:11], v[76:79], v[188:191], v[8:11]
	s_setprio 0
	s_setprio 1
	v_mfma_f32_16x16x32_bf16 v[52:55], v[144:147], v[160:163], v[52:55]
	v_mfma_f32_16x16x32_bf16 v[48:51], v[152:155], v[160:163], v[48:51]
	v_mfma_f32_16x16x32_bf16 v[36:39], v[144:147], v[168:171], v[36:39]
	v_mfma_f32_16x16x32_bf16 v[32:35], v[152:155], v[168:171], v[32:35]
	v_mfma_f32_16x16x32_bf16 v[20:23], v[144:147], v[176:179], v[20:23]
	v_mfma_f32_16x16x32_bf16 v[16:19], v[152:155], v[176:179], v[16:19]
	v_mfma_f32_16x16x32_bf16 v[4:7], v[144:147], v[184:187], v[4:7]
	v_mfma_f32_16x16x32_bf16 v[0:3], v[152:155], v[184:187], v[0:3]
	v_mfma_f32_16x16x32_bf16 v[52:55], v[148:151], v[164:167], v[52:55]
	v_mfma_f32_16x16x32_bf16 v[48:51], v[156:159], v[164:167], v[48:51]
	v_mfma_f32_16x16x32_bf16 v[36:39], v[148:151], v[172:175], v[36:39]
	v_mfma_f32_16x16x32_bf16 v[32:35], v[156:159], v[172:175], v[32:35]
	v_mfma_f32_16x16x32_bf16 v[20:23], v[148:151], v[180:183], v[20:23]
	v_mfma_f32_16x16x32_bf16 v[16:19], v[156:159], v[180:183], v[16:19]
	v_mfma_f32_16x16x32_bf16 v[4:7], v[148:151], v[188:191], v[4:7]
	v_mfma_f32_16x16x32_bf16 v[0:3], v[156:159], v[188:191], v[0:3]
	s_barrier
	s_setprio 0
	s_add_i32 s72, 0, 0x18000
	s_add_i32 s74, 0, 0x1c000
	v_add_u32_e32 v76, s72, v240
	v_add_u32_e32 v156, s74, v240
	ds_read_b128 v[64:67], v76
	ds_read_b128 v[68:71], v76 offset:1024
	ds_read_b128 v[72:75], v76 offset:2048
	ds_read_b128 v[76:79], v76 offset:3072
	ds_read_b128 v[144:147], v156
	ds_read_b128 v[148:151], v156 offset:1024
	ds_read_b128 v[152:155], v156 offset:2048
	ds_read_b128 v[156:159], v156 offset:3072
	s_add_u32 s34, s66, 0x80000
	s_addc_u32 s35, s67, 0
	s_mov_b32 m0, s82
	v_lshl_add_u64 v[200:201], s[34:35], 0, v[214:215]
	ds_read_b128 v[160:163], v241 offset:32768
	ds_read_b128 v[164:167], v241 offset:33792
	ds_read_b128 v[168:171], v241 offset:34816
	ds_read_b128 v[172:175], v241 offset:35840
	ds_read_b128 v[176:179], v241 offset:36864
	ds_read_b128 v[180:183], v241 offset:37888
	ds_read_b128 v[184:187], v241 offset:38912
	ds_read_b128 v[188:191], v241 offset:39936
	global_load_lds_dwordx4 v[200:201], off
	v_lshl_add_u64 v[200:201], s[34:35], 0, v[212:213]
	s_mov_b32 m0, s83
	s_nop 0
	global_load_lds_dwordx4 v[200:201], off
	s_waitcnt vmcnt(8)
	s_waitcnt lgkmcnt(0)
	s_setprio 1
	s_barrier
	s_waitcnt lgkmcnt(0)
	v_mfma_f32_16x16x32_bf16 v[140:143], v[64:67], v[160:163], v[140:143]
	v_mfma_f32_16x16x32_bf16 v[136:139], v[72:75], v[160:163], v[136:139]
	v_mfma_f32_16x16x32_bf16 v[124:127], v[64:67], v[168:171], v[124:127]
	v_mfma_f32_16x16x32_bf16 v[120:123], v[72:75], v[168:171], v[120:123]
	v_mfma_f32_16x16x32_bf16 v[108:111], v[64:67], v[176:179], v[108:111]
	v_mfma_f32_16x16x32_bf16 v[104:107], v[72:75], v[176:179], v[104:107]
	v_mfma_f32_16x16x32_bf16 v[92:95], v[64:67], v[184:187], v[92:95]
	v_mfma_f32_16x16x32_bf16 v[88:91], v[72:75], v[184:187], v[88:91]
	v_mfma_f32_16x16x32_bf16 v[140:143], v[68:71], v[164:167], v[140:143]
	v_mfma_f32_16x16x32_bf16 v[136:139], v[76:79], v[164:167], v[136:139]
	v_mfma_f32_16x16x32_bf16 v[124:127], v[68:71], v[172:175], v[124:127]
	v_mfma_f32_16x16x32_bf16 v[120:123], v[76:79], v[172:175], v[120:123]
	v_mfma_f32_16x16x32_bf16 v[108:111], v[68:71], v[180:183], v[108:111]
	v_mfma_f32_16x16x32_bf16 v[104:107], v[76:79], v[180:183], v[104:107]
	v_mfma_f32_16x16x32_bf16 v[92:95], v[68:71], v[188:191], v[92:95]
	v_mfma_f32_16x16x32_bf16 v[88:91], v[76:79], v[188:191], v[88:91]
	s_setprio 0
	s_setprio 1
	v_mfma_f32_16x16x32_bf16 v[132:135], v[144:147], v[160:163], v[132:135]
	v_mfma_f32_16x16x32_bf16 v[128:131], v[152:155], v[160:163], v[128:131]
	v_mfma_f32_16x16x32_bf16 v[116:119], v[144:147], v[168:171], v[116:119]
	v_mfma_f32_16x16x32_bf16 v[112:115], v[152:155], v[168:171], v[112:115]
	v_mfma_f32_16x16x32_bf16 v[100:103], v[144:147], v[176:179], v[100:103]
	v_mfma_f32_16x16x32_bf16 v[96:99], v[152:155], v[176:179], v[96:99]
	v_mfma_f32_16x16x32_bf16 v[84:87], v[144:147], v[184:187], v[84:87]
	v_mfma_f32_16x16x32_bf16 v[80:83], v[152:155], v[184:187], v[80:83]
	v_mfma_f32_16x16x32_bf16 v[132:135], v[148:151], v[164:167], v[132:135]
	v_mfma_f32_16x16x32_bf16 v[128:131], v[156:159], v[164:167], v[128:131]
	v_mfma_f32_16x16x32_bf16 v[116:119], v[148:151], v[172:175], v[116:119]
	v_mfma_f32_16x16x32_bf16 v[112:115], v[156:159], v[172:175], v[112:115]
	v_mfma_f32_16x16x32_bf16 v[100:103], v[148:151], v[180:183], v[100:103]
	v_mfma_f32_16x16x32_bf16 v[96:99], v[156:159], v[180:183], v[96:99]
	v_mfma_f32_16x16x32_bf16 v[84:87], v[148:151], v[188:191], v[84:87]
	v_mfma_f32_16x16x32_bf16 v[80:83], v[156:159], v[188:191], v[80:83]
	s_barrier
; #define PG8_STAGE(bufoff, gbase, voff) do { _Pragma("unroll") for (int _i = 0; _i < 2; ++_i) \
;         __builtin_amdgcn_global_load_lds((const unsigned*)((const char*)(gbase) + (voff)[_i]), (PG8_LAS unsigned*)(lds + (bufoff) + ldsw + _i * 8192), 16, 0, 0); } while (0)
; #define PG8_LDA(dst, b, h) do { _Pragma("unroll") for (int m = 0; m < 4; ++m) _Pragma("unroll") for (int k = 0; k < 2; ++k) dst[m][k] = *(const PG8_LAS bf16x8*)(lds + PG8_SA(b, h) + aoff + m * 2048 + k * 1024); } while (0)
; #define PG8_MMA(ai, bj, At, Bt) do { __builtin_amdgcn_s_setprio(1); _Pragma("unroll") for (int m = 0; m < 4; ++m) _Pragma("unroll") for (int n = 0; n < 2; ++n) _Pragma("unroll") for (int k = 0; k < 2; ++k) \
;         acc[ai][bj][m][n] = __builtin_amdgcn_mfma_f32_16x16x32_bf16(Bt[n][k], At[m][k], acc[ai][bj][m][n], 0, 0, 0); __builtin_amdgcn_s_setprio(0); } while (0)
; #define PG8_WAIT_V(n) asm volatile("s_waitcnt vmcnt(" #n ")" ::: "memory")
; #define PG8_WAIT_L(n) asm volatile("s_waitcnt lgkmcnt(" #n ")" ::: "memory")
; #define PG8_BAR __builtin_amdgcn_s_barrier()
; #define PG8_SCHED __builtin_amdgcn_sched_barrier(0)
; template <class Epi, class Sched, bool ALIGN_EPI = false, bool SP2 = false>
; __device__ __forceinline__ void gemm_phase(PG8_LAS unsigned char* lds, const Gemm g, const Sched& S, const Epi& E) {
;     ...
;         for (int t = 0; t < nt; t += 2) {
;     ...
;             PG8_LDA(At, 1, 1); PG8_STAGE(PG8_SB(1, 0), b3, voffB); PG8_STAGE(PG8_SB(1, 1), b3 + hstep, voffB); PG8_STAGE(PG8_SA(1, 0), a3, voffA);
;             PG8_WAIT_V(8); PG8_WAIT_L(0); PG8_BAR; PG8_MMA(1, 0, At, B0); PG8_MMA(1, 1, At, B1); PG8_BAR; PG8_SCHED;
	s_setprio 0
	s_add_i32 s34, s72, s79
	v_lshl_add_u64 v[192:193], v[192:193], 0, s[8:9]
	s_mov_b32 m0, s34
	ds_read_b128 v[160:163], v241 offset:49152
	ds_read_b128 v[164:167], v241 offset:50176
	ds_read_b128 v[168:171], v241 offset:51200
	ds_read_b128 v[172:175], v241 offset:52224
	ds_read_b128 v[176:179], v241 offset:53248
	ds_read_b128 v[180:183], v241 offset:54272
	ds_read_b128 v[184:187], v241 offset:55296
	ds_read_b128 v[188:191], v241 offset:56320
	global_load_lds_dwordx4 v[192:193], off
	s_add_i32 m0, s34, 0x2000
	s_add_u32 s34, s62, 0x80080
	v_lshl_add_u64 v[192:193], v[194:195], 0, s[8:9]
	s_addc_u32 s35, s63, 0
	s_add_i32 s62, s74, s79
	global_load_lds_dwordx4 v[192:193], off
	v_lshl_add_u64 v[192:193], s[34:35], 0, v[204:205]
	s_mov_b32 m0, s62
	s_nop 0
	global_load_lds_dwordx4 v[192:193], off
	v_lshl_add_u64 v[192:193], s[34:35], 0, v[210:211]
	s_add_i32 m0, s62, 0x2000
	s_nop 0
	global_load_lds_dwordx4 v[192:193], off
	v_lshl_add_u64 v[192:193], v[196:197], 0, s[8:9]
	s_mov_b32 m0, s89
	s_nop 0
	global_load_lds_dwordx4 v[192:193], off
	v_lshl_add_u64 v[192:193], v[198:199], 0, s[8:9]
	s_mov_b32 m0, s90
	s_nop 0
	global_load_lds_dwordx4 v[192:193], off
	s_waitcnt vmcnt(8)
	s_waitcnt lgkmcnt(0)
	s_setprio 1
	s_barrier
	s_waitcnt lgkmcnt(0)
	v_mfma_f32_16x16x32_bf16 v[60:63], v[64:67], v[160:163], v[60:63]
	v_mfma_f32_16x16x32_bf16 v[56:59], v[72:75], v[160:163], v[56:59]
	v_mfma_f32_16x16x32_bf16 v[44:47], v[64:67], v[168:171], v[44:47]
	v_mfma_f32_16x16x32_bf16 v[40:43], v[72:75], v[168:171], v[40:43]
	v_mfma_f32_16x16x32_bf16 v[28:31], v[64:67], v[176:179], v[28:31]
	v_mfma_f32_16x16x32_bf16 v[24:27], v[72:75], v[176:179], v[24:27]
	v_mfma_f32_16x16x32_bf16 v[12:15], v[64:67], v[184:187], v[12:15]
	v_mfma_f32_16x16x32_bf16 v[8:11], v[72:75], v[184:187], v[8:11]
	v_mfma_f32_16x16x32_bf16 v[60:63], v[68:71], v[164:167], v[60:63]
	v_mfma_f32_16x16x32_bf16 v[56:59], v[76:79], v[164:167], v[56:59]
	v_mfma_f32_16x16x32_bf16 v[44:47], v[68:71], v[172:175], v[44:47]
	v_mfma_f32_16x16x32_bf16 v[40:43], v[76:79], v[172:175], v[40:43]
	v_mfma_f32_16x16x32_bf16 v[28:31], v[68:71], v[180:183], v[28:31]
	v_mfma_f32_16x16x32_bf16 v[24:27], v[76:79], v[180:183], v[24:27]
	v_mfma_f32_16x16x32_bf16 v[12:15], v[68:71], v[188:191], v[12:15]
	v_mfma_f32_16x16x32_bf16 v[8:11], v[76:79], v[188:191], v[8:11]
	s_setprio 0
	s_setprio 1
	v_mfma_f32_16x16x32_bf16 v[52:55], v[144:147], v[160:163], v[52:55]
	v_mfma_f32_16x16x32_bf16 v[48:51], v[152:155], v[160:163], v[48:51]
	v_mfma_f32_16x16x32_bf16 v[36:39], v[144:147], v[168:171], v[36:39]
	v_mfma_f32_16x16x32_bf16 v[32:35], v[152:155], v[168:171], v[32:35]
	v_mfma_f32_16x16x32_bf16 v[20:23], v[144:147], v[176:179], v[20:23]
	v_mfma_f32_16x16x32_bf16 v[16:19], v[152:155], v[176:179], v[16:19]
	v_mfma_f32_16x16x32_bf16 v[4:7], v[144:147], v[184:187], v[4:7]
	v_mfma_f32_16x16x32_bf16 v[0:3], v[152:155], v[184:187], v[0:3]
	v_mfma_f32_16x16x32_bf16 v[52:55], v[148:151], v[164:167], v[52:55]
	v_mfma_f32_16x16x32_bf16 v[48:51], v[156:159], v[164:167], v[48:51]
	v_mfma_f32_16x16x32_bf16 v[36:39], v[148:151], v[172:175], v[36:39]
	v_mfma_f32_16x16x32_bf16 v[32:35], v[156:159], v[172:175], v[32:35]
	v_mfma_f32_16x16x32_bf16 v[20:23], v[148:151], v[180:183], v[20:23]
	v_mfma_f32_16x16x32_bf16 v[16:19], v[156:159], v[180:183], v[16:19]
	v_mfma_f32_16x16x32_bf16 v[4:7], v[148:151], v[188:191], v[4:7]
	v_mfma_f32_16x16x32_bf16 v[0:3], v[156:159], v[188:191], v[0:3]
	s_barrier
	s_setprio 0
	s_add_i32 vcc_hi, vcc_hi, 2
	s_add_u32 s6, s6, 0x100
	s_addc_u32 s7, s7, 0
	s_add_u32 s99, s99, 0x100
	s_addc_u32 vcc_lo, vcc_lo, 0
	s_cmp_gt_u32 vcc_hi, 29
	s_cbranch_scc0 .LBB0_311
	s_and_b64 vcc, exec, s[10:11]
	s_cbranch_vccz .LBB0_314
	s_barrier

; #define PG8_STAGE(bufoff, gbase, voff) do { _Pragma("unroll") for (int _i = 0; _i < 2; ++_i) \
;         __builtin_amdgcn_global_load_lds((const unsigned*)((const char*)(gbase) + (voff)[_i]), (PG8_LAS unsigned*)(lds + (bufoff) + ldsw + _i * 8192), 16, 0, 0); } while (0)
; #define PG8_LDA(dst, b, h) do { _Pragma("unroll") for (int m = 0; m < 4; ++m) _Pragma("unroll") for (int k = 0; k < 2; ++k) dst[m][k] = *(const PG8_LAS bf16x8*)(lds + PG8_SA(b, h) + aoff + m * 2048 + k * 1024); } while (0)
; #define PG8_LDB(dst, b, h) do { _Pragma("unroll") for (int n = 0; n < 2; ++n) _Pragma("unroll") for (int k = 0; k < 2; ++k) dst[n][k] = *(const PG8_LAS bf16x8*)(lds + PG8_SB(b, h) + boff + n * 2048 + k * 1024); } while (0)
; #define PG8_MMA(ai, bj, At, Bt) do { __builtin_amdgcn_s_setprio(1); _Pragma("unroll") for (int m = 0; m < 4; ++m) _Pragma("unroll") for (int n = 0; n < 2; ++n) _Pragma("unroll") for (int k = 0; k < 2; ++k) \
;         acc[ai][bj][m][n] = __builtin_amdgcn_mfma_f32_16x16x32_bf16(Bt[n][k], At[m][k], acc[ai][bj][m][n], 0, 0, 0); __builtin_amdgcn_s_setprio(0); } while (0)
; #define PG8_WAIT_V(n) asm volatile("s_waitcnt vmcnt(" #n ")" ::: "memory")
; #define PG8_WAIT_L(n) asm volatile("s_waitcnt lgkmcnt(" #n ")" ::: "memory")
; template <class Epi, class Sched, bool ALIGN_EPI = false, bool SP2 = false>
; __device__ __forceinline__ void gemm_phase(PG8_LAS unsigned char* lds, const Gemm g, const Sched& S, const Epi& E) {
;     ...
;             const bool last = (t == nt - 2);
;             const char* a1 = cA + (size_t)(t + 1) * kstep;
;             const char* a2 = last ? nA : cA + (size_t)(t + 2) * kstep; const char* b2 = last ? nB : cB + (size_t)(t + 2) * kstep;
;             const char* a3 = a2 + kstep; const char* b3 = b2 + kstep;
;             if (last && has_next) S.a_ready(nxt);
;             if constexpr (SP2) {
;             PG8_LDB(B0, 0, 0); PG8_LDB(B1, 0, 1); PG8_SCHED; PG8_LDA(At, 0, 0); PG8_STAGE(PG8_SA(1, 1), a1 + hstep, voffA);
;             PG8_WAIT_V(8); PG8_WAIT_L(0); PG8_BAR; PG8_MMA(0, 0, At, B0); PG8_MMA(0, 1, At, B1); PG8_BAR; PG8_SCHED;
;             PG8_LDA(At, 0, 1); PG8_STAGE(PG8_SB(0, 0), b2, voffB); PG8_STAGE(PG8_SB(0, 1), b2 + hstep, voffB); PG8_STAGE(PG8_SA(0, 0), a2, voffA);
;             PG8_WAIT_V(8); PG8_WAIT_L(0); PG8_BAR; PG8_MMA(1, 0, At, B0); PG8_MMA(1, 1, At, B1); PG8_BAR; PG8_SCHED;
.LBB0_422:
	s_add_u32 s34, s60, 0xfff80080
	s_addc_u32 s35, s61, -1
	s_add_i32 s72, 0, 0x10000
	s_cmp_eq_u32 s93, 28
	s_cselect_b32 s67, s43, s35
	s_cselect_b32 s66, s89, s34
	v_add_u32_e32 v138, s72, v142
	s_cselect_b32 s63, s19, s92
	s_cselect_b32 s62, s90, s91
	s_add_i32 s74, 0, 0x14000
	ds_read_b128 v[144:147], v138
	ds_read_b128 v[148:151], v138 offset:1024
	ds_read_b128 v[152:155], v138 offset:2048
	ds_read_b128 v[156:159], v138 offset:3072
	v_add_u32_e32 v138, s74, v142
	ds_read_b128 v[160:163], v138
	ds_read_b128 v[164:167], v138 offset:1024
	ds_read_b128 v[168:171], v138 offset:2048
	ds_read_b128 v[172:175], v138 offset:3072
	v_lshl_add_u64 v[138:139], s[60:61], 0, v[134:135]
	s_add_i32 m0, s78, 0xc000
	ds_read_b128 v[176:179], v143
	ds_read_b128 v[180:183], v143 offset:1024
	ds_read_b128 v[184:187], v143 offset:2048
	ds_read_b128 v[188:191], v143 offset:3072
	ds_read_b128 v[192:195], v143 offset:4096
	ds_read_b128 v[196:199], v143 offset:5120
	ds_read_b128 v[200:203], v143 offset:6144
	ds_read_b128 v[206:209], v143 offset:7168
	global_load_lds_dwordx4 v[138:139], off
	v_lshl_add_u64 v[138:139], s[60:61], 0, v[136:137]
	s_add_i32 m0, s78, 0xe000
	s_nop 0
	global_load_lds_dwordx4 v[138:139], off
	s_waitcnt vmcnt(8)
	s_waitcnt lgkmcnt(0)
	s_setprio 1
	s_barrier
	s_waitcnt lgkmcnt(0)
	v_mfma_f32_16x16x32_bf16 v[124:127], v[144:147], v[176:179], v[124:127]
	v_mfma_f32_16x16x32_bf16 v[120:123], v[152:155], v[176:179], v[120:123]
	v_mfma_f32_16x16x32_bf16 v[108:111], v[144:147], v[184:187], v[108:111]
	v_mfma_f32_16x16x32_bf16 v[104:107], v[152:155], v[184:187], v[104:107]
	v_mfma_f32_16x16x32_bf16 v[92:95], v[144:147], v[192:195], v[92:95]
	v_mfma_f32_16x16x32_bf16 v[88:91], v[152:155], v[192:195], v[88:91]
	v_mfma_f32_16x16x32_bf16 v[76:79], v[144:147], v[200:203], v[76:79]
	v_mfma_f32_16x16x32_bf16 v[72:75], v[152:155], v[200:203], v[72:75]
	v_mfma_f32_16x16x32_bf16 v[124:127], v[148:151], v[180:183], v[124:127]
	v_mfma_f32_16x16x32_bf16 v[120:123], v[156:159], v[180:183], v[120:123]
	v_mfma_f32_16x16x32_bf16 v[108:111], v[148:151], v[188:191], v[108:111]
	v_mfma_f32_16x16x32_bf16 v[104:107], v[156:159], v[188:191], v[104:107]
	v_mfma_f32_16x16x32_bf16 v[92:95], v[148:151], v[196:199], v[92:95]
	v_mfma_f32_16x16x32_bf16 v[88:91], v[156:159], v[196:199], v[88:91]
	v_mfma_f32_16x16x32_bf16 v[76:79], v[148:151], v[206:209], v[76:79]
	v_mfma_f32_16x16x32_bf16 v[72:75], v[156:159], v[206:209], v[72:75]
	s_setprio 0
	s_setprio 1
	v_mfma_f32_16x16x32_bf16 v[116:119], v[160:163], v[176:179], v[116:119]
	v_mfma_f32_16x16x32_bf16 v[112:115], v[168:171], v[176:179], v[112:115]
	v_mfma_f32_16x16x32_bf16 v[100:103], v[160:163], v[184:187], v[100:103]
	v_mfma_f32_16x16x32_bf16 v[96:99], v[168:171], v[184:187], v[96:99]
	v_mfma_f32_16x16x32_bf16 v[84:87], v[160:163], v[192:195], v[84:87]
	v_mfma_f32_16x16x32_bf16 v[80:83], v[168:171], v[192:195], v[80:83]
	v_mfma_f32_16x16x32_bf16 v[68:71], v[160:163], v[200:203], v[68:71]
	v_mfma_f32_16x16x32_bf16 v[64:67], v[168:171], v[200:203], v[64:67]
	v_mfma_f32_16x16x32_bf16 v[116:119], v[164:167], v[180:183], v[116:119]
	v_mfma_f32_16x16x32_bf16 v[112:115], v[172:175], v[180:183], v[112:115]
	v_mfma_f32_16x16x32_bf16 v[100:103], v[164:167], v[188:191], v[100:103]
	v_mfma_f32_16x16x32_bf16 v[96:99], v[172:175], v[188:191], v[96:99]
	v_mfma_f32_16x16x32_bf16 v[84:87], v[164:167], v[196:199], v[84:87]
	v_mfma_f32_16x16x32_bf16 v[80:83], v[172:175], v[196:199], v[80:83]
	v_mfma_f32_16x16x32_bf16 v[68:71], v[164:167], v[206:209], v[68:71]
	v_mfma_f32_16x16x32_bf16 v[64:67], v[172:175], v[206:209], v[64:67]
	s_barrier
	s_setprio 0
	s_add_i32 s34, s72, s69
	v_lshl_add_u64 v[138:139], s[62:63], 0, v[204:205]
	s_mov_b32 m0, s34
	ds_read_b128 v[176:179], v143 offset:16384
	ds_read_b128 v[180:183], v143 offset:17408
	ds_read_b128 v[184:187], v143 offset:18432
	ds_read_b128 v[188:191], v143 offset:19456
	ds_read_b128 v[192:195], v143 offset:20480
	ds_read_b128 v[196:199], v143 offset:21504
	ds_read_b128 v[200:203], v143 offset:22528
	ds_read_b128 v[206:209], v143 offset:23552
	global_load_lds_dwordx4 v[138:139], off
	s_add_i32 m0, s34, 0x2000
	s_add_u32 s34, s62, 0x80000
	v_lshl_add_u64 v[210:211], s[62:63], 0, v[128:129]
	s_addc_u32 s35, s63, 0
	s_add_i32 s72, s74, s69
	global_load_lds_dwordx4 v[210:211], off
	v_lshl_add_u64 v[212:213], s[34:35], 0, v[204:205]
	s_mov_b32 m0, s72
	v_lshl_add_u64 v[214:215], s[66:67], 0, v[130:131]
	global_load_lds_dwordx4 v[212:213], off
	v_lshl_add_u64 v[212:213], s[34:35], 0, v[128:129]
	s_add_i32 m0, s72, 0x2000
	s_nop 0
	global_load_lds_dwordx4 v[212:213], off
	v_lshl_add_u64 v[212:213], s[66:67], 0, v[132:133]
	s_mov_b32 m0, s78
	s_nop 0
	global_load_lds_dwordx4 v[212:213], off
	s_mov_b32 m0, s79
	s_nop 0
	global_load_lds_dwordx4 v[214:215], off
	s_waitcnt vmcnt(8)
	s_waitcnt lgkmcnt(0)
	s_setprio 1
	s_barrier
; #define PG8_STAGE(bufoff, gbase, voff) do { _Pragma("unroll") for (int _i = 0; _i < 2; ++_i) \
;         __builtin_amdgcn_global_load_lds((const unsigned*)((const char*)(gbase) + (voff)[_i]), (PG8_LAS unsigned*)(lds + (bufoff) + ldsw + _i * 8192), 16, 0, 0); } while (0)
; #define PG8_LDA(dst, b, h) do { _Pragma("unroll") for (int m = 0; m < 4; ++m) _Pragma("unroll") for (int k = 0; k < 2; ++k) dst[m][k] = *(const PG8_LAS bf16x8*)(lds + PG8_SA(b, h) + aoff + m * 2048 + k * 1024); } while (0)
; #define PG8_LDB(dst, b, h) do { _Pragma("unroll") for (int n = 0; n < 2; ++n) _Pragma("unroll") for (int k = 0; k < 2; ++k) dst[n][k] = *(const PG8_LAS bf16x8*)(lds + PG8_SB(b, h) + boff + n * 2048 + k * 1024); } while (0)
; #define PG8_MMA(ai, bj, At, Bt) do { __builtin_amdgcn_s_setprio(1); _Pragma("unroll") for (int m = 0; m < 4; ++m) _Pragma("unroll") for (int n = 0; n < 2; ++n) _Pragma("unroll") for (int k = 0; k < 2; ++k) \
;         acc[ai][bj][m][n] = __builtin_amdgcn_mfma_f32_16x16x32_bf16(Bt[n][k], At[m][k], acc[ai][bj][m][n], 0, 0, 0); __builtin_amdgcn_s_setprio(0); } while (0)
; #define PG8_WAIT_V(n) asm volatile("s_waitcnt vmcnt(" #n ")" ::: "memory")
; #define PG8_WAIT_L(n) asm volatile("s_waitcnt lgkmcnt(" #n ")" ::: "memory")
; #define PG8_BAR __builtin_amdgcn_s_barrier()
; #define PG8_SCHED __builtin_amdgcn_sched_barrier(0)
; template <class Epi, class Sched, bool ALIGN_EPI = false, bool SP2 = false>
; __device__ __forceinline__ void gemm_phase(PG8_LAS unsigned char* lds, const Gemm g, const Sched& S, const Epi& E) {
;     ...
;             PG8_WAIT_V(8); PG8_WAIT_L(0); PG8_BAR; PG8_MMA(1, 0, At, B0); PG8_MMA(1, 1, At, B1); PG8_BAR; PG8_SCHED;
;             PG8_LDB(B0, 1, 0); PG8_LDB(B1, 1, 1); PG8_SCHED; PG8_LDA(At, 1, 0); PG8_STAGE(PG8_SA(0, 1), a2 + hstep, voffA);
;             PG8_WAIT_V(8); PG8_WAIT_L(0); PG8_BAR; PG8_MMA(0, 0, At, B0); PG8_MMA(0, 1, At, B1); PG8_BAR; PG8_SCHED;
	s_waitcnt lgkmcnt(0)
	v_mfma_f32_16x16x32_bf16 v[60:63], v[144:147], v[176:179], v[60:63]
	v_mfma_f32_16x16x32_bf16 v[56:59], v[152:155], v[176:179], v[56:59]
	v_mfma_f32_16x16x32_bf16 v[44:47], v[144:147], v[184:187], v[44:47]
	v_mfma_f32_16x16x32_bf16 v[40:43], v[152:155], v[184:187], v[40:43]
	v_mfma_f32_16x16x32_bf16 v[28:31], v[144:147], v[192:195], v[28:31]
	v_mfma_f32_16x16x32_bf16 v[24:27], v[152:155], v[192:195], v[24:27]
	v_mfma_f32_16x16x32_bf16 v[12:15], v[144:147], v[200:203], v[12:15]
	v_mfma_f32_16x16x32_bf16 v[8:11], v[152:155], v[200:203], v[8:11]
	v_mfma_f32_16x16x32_bf16 v[60:63], v[148:151], v[180:183], v[60:63]
	v_mfma_f32_16x16x32_bf16 v[56:59], v[156:159], v[180:183], v[56:59]
	v_mfma_f32_16x16x32_bf16 v[44:47], v[148:151], v[188:191], v[44:47]
	v_mfma_f32_16x16x32_bf16 v[40:43], v[156:159], v[188:191], v[40:43]
	v_mfma_f32_16x16x32_bf16 v[28:31], v[148:151], v[196:199], v[28:31]
	v_mfma_f32_16x16x32_bf16 v[24:27], v[156:159], v[196:199], v[24:27]
	v_mfma_f32_16x16x32_bf16 v[12:15], v[148:151], v[206:209], v[12:15]
	v_mfma_f32_16x16x32_bf16 v[8:11], v[156:159], v[206:209], v[8:11]
	s_setprio 0
	s_setprio 1
	v_mfma_f32_16x16x32_bf16 v[52:55], v[160:163], v[176:179], v[52:55]
	v_mfma_f32_16x16x32_bf16 v[48:51], v[168:171], v[176:179], v[48:51]
	v_mfma_f32_16x16x32_bf16 v[36:39], v[160:163], v[184:187], v[36:39]
	v_mfma_f32_16x16x32_bf16 v[32:35], v[168:171], v[184:187], v[32:35]
	v_mfma_f32_16x16x32_bf16 v[20:23], v[160:163], v[192:195], v[20:23]
	v_mfma_f32_16x16x32_bf16 v[16:19], v[168:171], v[192:195], v[16:19]
	v_mfma_f32_16x16x32_bf16 v[4:7], v[160:163], v[200:203], v[4:7]
	v_mfma_f32_16x16x32_bf16 v[0:3], v[168:171], v[200:203], v[0:3]
	v_mfma_f32_16x16x32_bf16 v[52:55], v[164:167], v[180:183], v[52:55]
	v_mfma_f32_16x16x32_bf16 v[48:51], v[172:175], v[180:183], v[48:51]
	v_mfma_f32_16x16x32_bf16 v[36:39], v[164:167], v[188:191], v[36:39]
	v_mfma_f32_16x16x32_bf16 v[32:35], v[172:175], v[188:191], v[32:35]
	v_mfma_f32_16x16x32_bf16 v[20:23], v[164:167], v[196:199], v[20:23]
	v_mfma_f32_16x16x32_bf16 v[16:19], v[172:175], v[196:199], v[16:19]
	v_mfma_f32_16x16x32_bf16 v[4:7], v[164:167], v[206:209], v[4:7]
	v_mfma_f32_16x16x32_bf16 v[0:3], v[172:175], v[206:209], v[0:3]
	s_barrier
	s_setprio 0
	s_add_i32 s72, 0, 0x18000
	s_add_i32 s74, 0, 0x1c000
	v_add_u32_e32 v156, s72, v142
	v_add_u32_e32 v172, s74, v142
	ds_read_b128 v[144:147], v156
	ds_read_b128 v[148:151], v156 offset:1024
	ds_read_b128 v[152:155], v156 offset:2048
	ds_read_b128 v[156:159], v156 offset:3072
	ds_read_b128 v[160:163], v172
	ds_read_b128 v[164:167], v172 offset:1024
	ds_read_b128 v[168:171], v172 offset:2048
	ds_read_b128 v[172:175], v172 offset:3072
	s_add_u32 s34, s66, 0x80000
	s_addc_u32 s35, s67, 0
	s_mov_b32 m0, s80
	v_lshl_add_u64 v[216:217], s[34:35], 0, v[132:133]
	ds_read_b128 v[176:179], v143 offset:32768
	ds_read_b128 v[180:183], v143 offset:33792
	ds_read_b128 v[184:187], v143 offset:34816
	ds_read_b128 v[188:191], v143 offset:35840
	ds_read_b128 v[192:195], v143 offset:36864
	ds_read_b128 v[196:199], v143 offset:37888
	ds_read_b128 v[200:203], v143 offset:38912
	ds_read_b128 v[206:209], v143 offset:39936
	global_load_lds_dwordx4 v[216:217], off
	v_lshl_add_u64 v[216:217], s[34:35], 0, v[130:131]
	s_mov_b32 m0, s81
	s_nop 0
	global_load_lds_dwordx4 v[216:217], off
	s_waitcnt vmcnt(8)
	s_waitcnt lgkmcnt(0)
	s_setprio 1
	s_barrier
	s_waitcnt lgkmcnt(0)
	v_mfma_f32_16x16x32_bf16 v[124:127], v[144:147], v[176:179], v[124:127]
	v_mfma_f32_16x16x32_bf16 v[120:123], v[152:155], v[176:179], v[120:123]
	v_mfma_f32_16x16x32_bf16 v[108:111], v[144:147], v[184:187], v[108:111]
	v_mfma_f32_16x16x32_bf16 v[104:107], v[152:155], v[184:187], v[104:107]
	v_mfma_f32_16x16x32_bf16 v[92:95], v[144:147], v[192:195], v[92:95]
	v_mfma_f32_16x16x32_bf16 v[88:91], v[152:155], v[192:195], v[88:91]
	v_mfma_f32_16x16x32_bf16 v[76:79], v[144:147], v[200:203], v[76:79]
	v_mfma_f32_16x16x32_bf16 v[72:75], v[152:155], v[200:203], v[72:75]
	v_mfma_f32_16x16x32_bf16 v[124:127], v[148:151], v[180:183], v[124:127]
	v_mfma_f32_16x16x32_bf16 v[120:123], v[156:159], v[180:183], v[120:123]
	v_mfma_f32_16x16x32_bf16 v[108:111], v[148:151], v[188:191], v[108:111]
	v_mfma_f32_16x16x32_bf16 v[104:107], v[156:159], v[188:191], v[104:107]
	v_mfma_f32_16x16x32_bf16 v[92:95], v[148:151], v[196:199], v[92:95]
	v_mfma_f32_16x16x32_bf16 v[88:91], v[156:159], v[196:199], v[88:91]
	v_mfma_f32_16x16x32_bf16 v[76:79], v[148:151], v[206:209], v[76:79]
	v_mfma_f32_16x16x32_bf16 v[72:75], v[156:159], v[206:209], v[72:75]
	s_setprio 0
	s_setprio 1
	v_mfma_f32_16x16x32_bf16 v[116:119], v[160:163], v[176:179], v[116:119]
	v_mfma_f32_16x16x32_bf16 v[112:115], v[168:171], v[176:179], v[112:115]
	v_mfma_f32_16x16x32_bf16 v[100:103], v[160:163], v[184:187], v[100:103]
	v_mfma_f32_16x16x32_bf16 v[96:99], v[168:171], v[184:187], v[96:99]
	v_mfma_f32_16x16x32_bf16 v[84:87], v[160:163], v[192:195], v[84:87]
	v_mfma_f32_16x16x32_bf16 v[80:83], v[168:171], v[192:195], v[80:83]
	v_mfma_f32_16x16x32_bf16 v[68:71], v[160:163], v[200:203], v[68:71]
	v_mfma_f32_16x16x32_bf16 v[64:67], v[168:171], v[200:203], v[64:67]
	v_mfma_f32_16x16x32_bf16 v[116:119], v[164:167], v[180:183], v[116:119]
	v_mfma_f32_16x16x32_bf16 v[112:115], v[172:175], v[180:183], v[112:115]
	v_mfma_f32_16x16x32_bf16 v[100:103], v[164:167], v[188:191], v[100:103]
	v_mfma_f32_16x16x32_bf16 v[96:99], v[172:175], v[188:191], v[96:99]
	v_mfma_f32_16x16x32_bf16 v[84:87], v[164:167], v[196:199], v[84:87]
	v_mfma_f32_16x16x32_bf16 v[80:83], v[172:175], v[196:199], v[80:83]
	v_mfma_f32_16x16x32_bf16 v[68:71], v[164:167], v[206:209], v[68:71]
	v_mfma_f32_16x16x32_bf16 v[64:67], v[172:175], v[206:209], v[64:67]
	s_barrier
; #define PG8_STAGE(bufoff, gbase, voff) do { _Pragma("unroll") for (int _i = 0; _i < 2; ++_i) \
;         __builtin_amdgcn_global_load_lds((const unsigned*)((const char*)(gbase) + (voff)[_i]), (PG8_LAS unsigned*)(lds + (bufoff) + ldsw + _i * 8192), 16, 0, 0); } while (0)
; #define PG8_LDA(dst, b, h) do { _Pragma("unroll") for (int m = 0; m < 4; ++m) _Pragma("unroll") for (int k = 0; k < 2; ++k) dst[m][k] = *(const PG8_LAS bf16x8*)(lds + PG8_SA(b, h) + aoff + m * 2048 + k * 1024); } while (0)
; #define PG8_MMA(ai, bj, At, Bt) do { __builtin_amdgcn_s_setprio(1); _Pragma("unroll") for (int m = 0; m < 4; ++m) _Pragma("unroll") for (int n = 0; n < 2; ++n) _Pragma("unroll") for (int k = 0; k < 2; ++k) \
;         acc[ai][bj][m][n] = __builtin_amdgcn_mfma_f32_16x16x32_bf16(Bt[n][k], At[m][k], acc[ai][bj][m][n], 0, 0, 0); __builtin_amdgcn_s_setprio(0); } while (0)
; #define PG8_WAIT_V(n) asm volatile("s_waitcnt vmcnt(" #n ")" ::: "memory")
; #define PG8_WAIT_L(n) asm volatile("s_waitcnt lgkmcnt(" #n ")" ::: "memory")
; #define PG8_BAR __builtin_amdgcn_s_barrier()
; #define PG8_SCHED __builtin_amdgcn_sched_barrier(0)
; template <class Epi, class Sched, bool ALIGN_EPI = false, bool SP2 = false>
; __device__ __forceinline__ void gemm_phase(PG8_LAS unsigned char* lds, const Gemm g, const Sched& S, const Epi& E) {
;     ...
;             PG8_LDA(At, 1, 1); PG8_STAGE(PG8_SB(1, 0), b3, voffB); PG8_STAGE(PG8_SB(1, 1), b3 + hstep, voffB); PG8_STAGE(PG8_SA(1, 0), a3, voffA);
;             PG8_WAIT_V(8); PG8_WAIT_L(0); PG8_BAR; PG8_MMA(1, 0, At, B0); PG8_MMA(1, 1, At, B1); PG8_BAR; PG8_SCHED;
;     ...
;         if constexpr (ALIGN_EPI) { if (wr == 0) PG8_BAR; }
	s_setprio 0
	s_add_i32 s34, s72, s69
	v_lshl_add_u64 v[138:139], v[138:139], 0, s[8:9]
	s_mov_b32 m0, s34
	ds_read_b128 v[176:179], v143 offset:49152
	ds_read_b128 v[180:183], v143 offset:50176
	ds_read_b128 v[184:187], v143 offset:51200
	ds_read_b128 v[188:191], v143 offset:52224
	ds_read_b128 v[192:195], v143 offset:53248
	ds_read_b128 v[196:199], v143 offset:54272
	ds_read_b128 v[200:203], v143 offset:55296
	ds_read_b128 v[206:209], v143 offset:56320
	global_load_lds_dwordx4 v[138:139], off
	s_add_i32 m0, s34, 0x2000
	s_add_u32 s34, s62, 0x80080
	v_lshl_add_u64 v[138:139], v[210:211], 0, s[8:9]
	s_addc_u32 s35, s63, 0
	s_add_i32 s62, s74, s69
	global_load_lds_dwordx4 v[138:139], off
	v_lshl_add_u64 v[138:139], s[34:35], 0, v[204:205]
	s_mov_b32 m0, s62
	s_nop 0
	global_load_lds_dwordx4 v[138:139], off
	v_lshl_add_u64 v[138:139], s[34:35], 0, v[128:129]
	s_add_i32 m0, s62, 0x2000
	s_nop 0
	global_load_lds_dwordx4 v[138:139], off
	v_lshl_add_u64 v[138:139], v[212:213], 0, s[8:9]
	s_mov_b32 m0, s84
	s_nop 0
	global_load_lds_dwordx4 v[138:139], off
	v_lshl_add_u64 v[138:139], v[214:215], 0, s[8:9]
	s_mov_b32 m0, s85
	s_nop 0
	global_load_lds_dwordx4 v[138:139], off
	s_waitcnt vmcnt(8)
	s_waitcnt lgkmcnt(0)
	s_setprio 1
	s_barrier
	s_waitcnt lgkmcnt(0)
	v_mfma_f32_16x16x32_bf16 v[60:63], v[144:147], v[176:179], v[60:63]
	v_mfma_f32_16x16x32_bf16 v[56:59], v[152:155], v[176:179], v[56:59]
	v_mfma_f32_16x16x32_bf16 v[44:47], v[144:147], v[184:187], v[44:47]
	v_mfma_f32_16x16x32_bf16 v[40:43], v[152:155], v[184:187], v[40:43]
	v_mfma_f32_16x16x32_bf16 v[28:31], v[144:147], v[192:195], v[28:31]
	v_mfma_f32_16x16x32_bf16 v[24:27], v[152:155], v[192:195], v[24:27]
	v_mfma_f32_16x16x32_bf16 v[12:15], v[144:147], v[200:203], v[12:15]
	v_mfma_f32_16x16x32_bf16 v[8:11], v[152:155], v[200:203], v[8:11]
	v_mfma_f32_16x16x32_bf16 v[60:63], v[148:151], v[180:183], v[60:63]
	v_mfma_f32_16x16x32_bf16 v[56:59], v[156:159], v[180:183], v[56:59]
	v_mfma_f32_16x16x32_bf16 v[44:47], v[148:151], v[188:191], v[44:47]
	v_mfma_f32_16x16x32_bf16 v[40:43], v[156:159], v[188:191], v[40:43]
	v_mfma_f32_16x16x32_bf16 v[28:31], v[148:151], v[196:199], v[28:31]
	v_mfma_f32_16x16x32_bf16 v[24:27], v[156:159], v[196:199], v[24:27]
	v_mfma_f32_16x16x32_bf16 v[12:15], v[148:151], v[206:209], v[12:15]
	v_mfma_f32_16x16x32_bf16 v[8:11], v[156:159], v[206:209], v[8:11]
	s_setprio 0
	s_setprio 1
	v_mfma_f32_16x16x32_bf16 v[52:55], v[160:163], v[176:179], v[52:55]
	v_mfma_f32_16x16x32_bf16 v[48:51], v[168:171], v[176:179], v[48:51]
	v_mfma_f32_16x16x32_bf16 v[36:39], v[160:163], v[184:187], v[36:39]
	v_mfma_f32_16x16x32_bf16 v[32:35], v[168:171], v[184:187], v[32:35]
	v_mfma_f32_16x16x32_bf16 v[20:23], v[160:163], v[192:195], v[20:23]
	v_mfma_f32_16x16x32_bf16 v[16:19], v[168:171], v[192:195], v[16:19]
	v_mfma_f32_16x16x32_bf16 v[4:7], v[160:163], v[200:203], v[4:7]
	v_mfma_f32_16x16x32_bf16 v[0:3], v[168:171], v[200:203], v[0:3]
	v_mfma_f32_16x16x32_bf16 v[52:55], v[164:167], v[180:183], v[52:55]
	v_mfma_f32_16x16x32_bf16 v[48:51], v[172:175], v[180:183], v[48:51]
	v_mfma_f32_16x16x32_bf16 v[36:39], v[164:167], v[188:191], v[36:39]
	v_mfma_f32_16x16x32_bf16 v[32:35], v[172:175], v[188:191], v[32:35]
	v_mfma_f32_16x16x32_bf16 v[20:23], v[164:167], v[196:199], v[20:23]
	v_mfma_f32_16x16x32_bf16 v[16:19], v[172:175], v[196:199], v[16:19]
	v_mfma_f32_16x16x32_bf16 v[4:7], v[164:167], v[206:209], v[4:7]
	v_mfma_f32_16x16x32_bf16 v[0:3], v[172:175], v[206:209], v[0:3]
	s_barrier
	s_setprio 0
	s_add_i32 s93, s93, 2
	s_add_u32 s60, s60, 0x100
	s_addc_u32 s61, s61, 0
	s_add_u32 s91, s91, 0x100
	s_addc_u32 s92, s92, 0
	s_cmp_gt_u32 s93, 29
	s_cbranch_scc0 .LBB0_422
	s_and_b64 vcc, exec, s[10:11]
	s_cbranch_vccz .LBB0_425
	s_barrier

; #define PG8_STAGE(bufoff, gbase, voff) do { _Pragma("unroll") for (int _i = 0; _i < 2; ++_i) \
;         __builtin_amdgcn_global_load_lds((const unsigned*)((const char*)(gbase) + (voff)[_i]), (PG8_LAS unsigned*)(lds + (bufoff) + ldsw + _i * 8192), 16, 0, 0); } while (0)
; #define PG8_LDA(dst, b, h) do { _Pragma("unroll") for (int m = 0; m < 4; ++m) _Pragma("unroll") for (int k = 0; k < 2; ++k) dst[m][k] = *(const PG8_LAS bf16x8*)(lds + PG8_SA(b, h) + aoff + m * 2048 + k * 1024); } while (0)
; #define PG8_LDB(dst, b, h) do { _Pragma("unroll") for (int n = 0; n < 2; ++n) _Pragma("unroll") for (int k = 0; k < 2; ++k) dst[n][k] = *(const PG8_LAS bf16x8*)(lds + PG8_SB(b, h) + boff + n * 2048 + k * 1024); } while (0)
; #define PG8_MMA(ai, bj, At, Bt) do { __builtin_amdgcn_s_setprio(1); _Pragma("unroll") for (int m = 0; m < 4; ++m) _Pragma("unroll") for (int n = 0; n < 2; ++n) _Pragma("unroll") for (int k = 0; k < 2; ++k) \
;         acc[ai][bj][m][n] = __builtin_amdgcn_mfma_f32_16x16x32_bf16(Bt[n][k], At[m][k], acc[ai][bj][m][n], 0, 0, 0); __builtin_amdgcn_s_setprio(0); } while (0)
; #define PG8_WAIT_V(n) asm volatile("s_waitcnt vmcnt(" #n ")" ::: "memory")
; #define PG8_WAIT_L(n) asm volatile("s_waitcnt lgkmcnt(" #n ")" ::: "memory")
; template <class Epi, class Sched, bool ALIGN_EPI = false, bool SP2 = false>
; __device__ __forceinline__ void gemm_phase(PG8_LAS unsigned char* lds, const Gemm g, const Sched& S, const Epi& E) {
;     ...
;             const bool last = (t == nt - 2);
;             const char* a1 = cA + (size_t)(t + 1) * kstep;
;             const char* a2 = last ? nA : cA + (size_t)(t + 2) * kstep; const char* b2 = last ? nB : cB + (size_t)(t + 2) * kstep;
;             const char* a3 = a2 + kstep; const char* b3 = b2 + kstep;
;             if (last && has_next) S.a_ready(nxt);
;             if constexpr (SP2) {
;             PG8_LDB(B0, 0, 0); PG8_LDB(B1, 0, 1); PG8_SCHED; PG8_LDA(At, 0, 0); PG8_STAGE(PG8_SA(1, 1), a1 + hstep, voffA);
;             PG8_WAIT_V(8); PG8_WAIT_L(0); PG8_BAR; PG8_MMA(0, 0, At, B0); PG8_MMA(0, 1, At, B1); PG8_BAR; PG8_SCHED;
;             PG8_LDA(At, 0, 1); PG8_STAGE(PG8_SB(0, 0), b2, voffB); PG8_STAGE(PG8_SB(0, 1), b2 + hstep, voffB); PG8_STAGE(PG8_SA(0, 0), a2, voffA);
;             PG8_WAIT_V(8); PG8_WAIT_L(0); PG8_BAR; PG8_MMA(1, 0, At, B0); PG8_MMA(1, 1, At, B1); PG8_BAR; PG8_SCHED;
.LBB0_493:
	s_add_u32 s34, s4, 0xffe00080
	s_addc_u32 s35, s5, -1
	s_add_i32 s72, 0, 0x10000
	s_cmpk_eq_i32 vcc_hi, 0x7c
	s_cselect_b32 s69, s49, s35
	s_cselect_b32 s68, s92, s34
	s_cselect_b32 s67, s57, vcc_lo
	s_cselect_b32 s66, s93, s99
	s_add_i32 s74, 0, 0x14000
	v_add_u32_e32 v76, s72, v244
	v_add_u32_e32 v156, s74, v244
	ds_read_b128 v[64:67], v76
	ds_read_b128 v[68:71], v76 offset:1024
	ds_read_b128 v[72:75], v76 offset:2048
	ds_read_b128 v[76:79], v76 offset:3072
	ds_read_b128 v[144:147], v156
	ds_read_b128 v[148:151], v156 offset:1024
	ds_read_b128 v[152:155], v156 offset:2048
	ds_read_b128 v[156:159], v156 offset:3072
	v_lshl_add_u64 v[192:193], s[4:5], 0, v[216:217]
	s_add_i32 m0, s81, 0xc000
	ds_read_b128 v[160:163], v245
	ds_read_b128 v[164:167], v245 offset:1024
	ds_read_b128 v[168:171], v245 offset:2048
	ds_read_b128 v[172:175], v245 offset:3072
	ds_read_b128 v[176:179], v245 offset:4096
	ds_read_b128 v[180:183], v245 offset:5120
	ds_read_b128 v[184:187], v245 offset:6144
	ds_read_b128 v[188:191], v245 offset:7168
	global_load_lds_dwordx4 v[192:193], off
	v_lshl_add_u64 v[192:193], s[4:5], 0, v[218:219]
	s_add_i32 m0, s81, 0xe000
	s_nop 0
	global_load_lds_dwordx4 v[192:193], off
	s_waitcnt vmcnt(8)
	s_waitcnt lgkmcnt(0)
	s_setprio 1
	s_barrier
	s_waitcnt lgkmcnt(0)
	v_mfma_f32_16x16x32_bf16 v[140:143], v[64:67], v[160:163], v[140:143]
	v_mfma_f32_16x16x32_bf16 v[136:139], v[72:75], v[160:163], v[136:139]
	v_mfma_f32_16x16x32_bf16 v[124:127], v[64:67], v[168:171], v[124:127]
	v_mfma_f32_16x16x32_bf16 v[120:123], v[72:75], v[168:171], v[120:123]
	v_mfma_f32_16x16x32_bf16 v[108:111], v[64:67], v[176:179], v[108:111]
	v_mfma_f32_16x16x32_bf16 v[104:107], v[72:75], v[176:179], v[104:107]
	v_mfma_f32_16x16x32_bf16 v[92:95], v[64:67], v[184:187], v[92:95]
	v_mfma_f32_16x16x32_bf16 v[88:91], v[72:75], v[184:187], v[88:91]
	v_mfma_f32_16x16x32_bf16 v[140:143], v[68:71], v[164:167], v[140:143]
	v_mfma_f32_16x16x32_bf16 v[136:139], v[76:79], v[164:167], v[136:139]
	v_mfma_f32_16x16x32_bf16 v[124:127], v[68:71], v[172:175], v[124:127]
	v_mfma_f32_16x16x32_bf16 v[120:123], v[76:79], v[172:175], v[120:123]
	v_mfma_f32_16x16x32_bf16 v[108:111], v[68:71], v[180:183], v[108:111]
	v_mfma_f32_16x16x32_bf16 v[104:107], v[76:79], v[180:183], v[104:107]
	v_mfma_f32_16x16x32_bf16 v[92:95], v[68:71], v[188:191], v[92:95]
	v_mfma_f32_16x16x32_bf16 v[88:91], v[76:79], v[188:191], v[88:91]
	s_setprio 0
	s_setprio 1
	v_mfma_f32_16x16x32_bf16 v[132:135], v[144:147], v[160:163], v[132:135]
	v_mfma_f32_16x16x32_bf16 v[128:131], v[152:155], v[160:163], v[128:131]
	v_mfma_f32_16x16x32_bf16 v[116:119], v[144:147], v[168:171], v[116:119]
	v_mfma_f32_16x16x32_bf16 v[112:115], v[152:155], v[168:171], v[112:115]
	v_mfma_f32_16x16x32_bf16 v[100:103], v[144:147], v[176:179], v[100:103]
	v_mfma_f32_16x16x32_bf16 v[96:99], v[152:155], v[176:179], v[96:99]
	v_mfma_f32_16x16x32_bf16 v[84:87], v[144:147], v[184:187], v[84:87]
	v_mfma_f32_16x16x32_bf16 v[80:83], v[152:155], v[184:187], v[80:83]
	v_mfma_f32_16x16x32_bf16 v[132:135], v[148:151], v[164:167], v[132:135]
	v_mfma_f32_16x16x32_bf16 v[128:131], v[156:159], v[164:167], v[128:131]
	v_mfma_f32_16x16x32_bf16 v[116:119], v[148:151], v[172:175], v[116:119]
	v_mfma_f32_16x16x32_bf16 v[112:115], v[156:159], v[172:175], v[112:115]
	v_mfma_f32_16x16x32_bf16 v[100:103], v[148:151], v[180:183], v[100:103]
	v_mfma_f32_16x16x32_bf16 v[96:99], v[156:159], v[180:183], v[96:99]
	v_mfma_f32_16x16x32_bf16 v[84:87], v[148:151], v[188:191], v[84:87]
	v_mfma_f32_16x16x32_bf16 v[80:83], v[156:159], v[188:191], v[80:83]
	s_barrier
	s_setprio 0
	s_add_i32 s34, s72, s80
	v_lshl_add_u64 v[192:193], s[66:67], 0, v[204:205]
	s_mov_b32 m0, s34
	ds_read_b128 v[160:163], v245 offset:16384
	ds_read_b128 v[164:167], v245 offset:17408
	ds_read_b128 v[168:171], v245 offset:18432
	ds_read_b128 v[172:175], v245 offset:19456
	ds_read_b128 v[176:179], v245 offset:20480
	ds_read_b128 v[180:183], v245 offset:21504
	ds_read_b128 v[184:187], v245 offset:22528
	ds_read_b128 v[188:191], v245 offset:23552
	global_load_lds_dwordx4 v[192:193], off
	s_add_i32 m0, s34, 0x2000
	s_add_u32 s34, s66, 0x200000
	v_lshl_add_u64 v[194:195], s[66:67], 0, v[210:211]
	s_addc_u32 s35, s67, 0
	s_add_i32 s72, s74, s80
	global_load_lds_dwordx4 v[194:195], off
	v_lshl_add_u64 v[196:197], s[34:35], 0, v[204:205]
	s_mov_b32 m0, s72
	v_lshl_add_u64 v[198:199], s[68:69], 0, v[212:213]
	global_load_lds_dwordx4 v[196:197], off
	v_lshl_add_u64 v[196:197], s[34:35], 0, v[210:211]
	s_add_i32 m0, s72, 0x2000
	s_nop 0
	global_load_lds_dwordx4 v[196:197], off
	v_lshl_add_u64 v[196:197], s[68:69], 0, v[214:215]
	s_mov_b32 m0, s81
	s_nop 0
	global_load_lds_dwordx4 v[196:197], off
	s_mov_b32 m0, s82
	s_nop 0
	global_load_lds_dwordx4 v[198:199], off
	s_waitcnt vmcnt(8)
	s_waitcnt lgkmcnt(0)
	s_setprio 1
	s_barrier
; #define PG8_STAGE(bufoff, gbase, voff) do { _Pragma("unroll") for (int _i = 0; _i < 2; ++_i) \
;         __builtin_amdgcn_global_load_lds((const unsigned*)((const char*)(gbase) + (voff)[_i]), (PG8_LAS unsigned*)(lds + (bufoff) + ldsw + _i * 8192), 16, 0, 0); } while (0)
; #define PG8_LDA(dst, b, h) do { _Pragma("unroll") for (int m = 0; m < 4; ++m) _Pragma("unroll") for (int k = 0; k < 2; ++k) dst[m][k] = *(const PG8_LAS bf16x8*)(lds + PG8_SA(b, h) + aoff + m * 2048 + k * 1024); } while (0)
; #define PG8_LDB(dst, b, h) do { _Pragma("unroll") for (int n = 0; n < 2; ++n) _Pragma("unroll") for (int k = 0; k < 2; ++k) dst[n][k] = *(const PG8_LAS bf16x8*)(lds + PG8_SB(b, h) + boff + n * 2048 + k * 1024); } while (0)
; #define PG8_MMA(ai, bj, At, Bt) do { __builtin_amdgcn_s_setprio(1); _Pragma("unroll") for (int m = 0; m < 4; ++m) _Pragma("unroll") for (int n = 0; n < 2; ++n) _Pragma("unroll") for (int k = 0; k < 2; ++k) \
;         acc[ai][bj][m][n] = __builtin_amdgcn_mfma_f32_16x16x32_bf16(Bt[n][k], At[m][k], acc[ai][bj][m][n], 0, 0, 0); __builtin_amdgcn_s_setprio(0); } while (0)
; #define PG8_WAIT_V(n) asm volatile("s_waitcnt vmcnt(" #n ")" ::: "memory")
; #define PG8_WAIT_L(n) asm volatile("s_waitcnt lgkmcnt(" #n ")" ::: "memory")
; #define PG8_BAR __builtin_amdgcn_s_barrier()
; #define PG8_SCHED __builtin_amdgcn_sched_barrier(0)
; template <class Epi, class Sched, bool ALIGN_EPI = false, bool SP2 = false>
; __device__ __forceinline__ void gemm_phase(PG8_LAS unsigned char* lds, const Gemm g, const Sched& S, const Epi& E) {
;     ...
;             PG8_WAIT_V(8); PG8_WAIT_L(0); PG8_BAR; PG8_MMA(1, 0, At, B0); PG8_MMA(1, 1, At, B1); PG8_BAR; PG8_SCHED;
;             PG8_LDB(B0, 1, 0); PG8_LDB(B1, 1, 1); PG8_SCHED; PG8_LDA(At, 1, 0); PG8_STAGE(PG8_SA(0, 1), a2 + hstep, voffA);
;             PG8_WAIT_V(8); PG8_WAIT_L(0); PG8_BAR; PG8_MMA(0, 0, At, B0); PG8_MMA(0, 1, At, B1); PG8_BAR; PG8_SCHED;
	s_waitcnt lgkmcnt(0)
	v_mfma_f32_16x16x32_bf16 v[60:63], v[64:67], v[160:163], v[60:63]
	v_mfma_f32_16x16x32_bf16 v[56:59], v[72:75], v[160:163], v[56:59]
	v_mfma_f32_16x16x32_bf16 v[44:47], v[64:67], v[168:171], v[44:47]
	v_mfma_f32_16x16x32_bf16 v[40:43], v[72:75], v[168:171], v[40:43]
	v_mfma_f32_16x16x32_bf16 v[28:31], v[64:67], v[176:179], v[28:31]
	v_mfma_f32_16x16x32_bf16 v[24:27], v[72:75], v[176:179], v[24:27]
	v_mfma_f32_16x16x32_bf16 v[12:15], v[64:67], v[184:187], v[12:15]
	v_mfma_f32_16x16x32_bf16 v[8:11], v[72:75], v[184:187], v[8:11]
	v_mfma_f32_16x16x32_bf16 v[60:63], v[68:71], v[164:167], v[60:63]
	v_mfma_f32_16x16x32_bf16 v[56:59], v[76:79], v[164:167], v[56:59]
	v_mfma_f32_16x16x32_bf16 v[44:47], v[68:71], v[172:175], v[44:47]
	v_mfma_f32_16x16x32_bf16 v[40:43], v[76:79], v[172:175], v[40:43]
	v_mfma_f32_16x16x32_bf16 v[28:31], v[68:71], v[180:183], v[28:31]
	v_mfma_f32_16x16x32_bf16 v[24:27], v[76:79], v[180:183], v[24:27]
	v_mfma_f32_16x16x32_bf16 v[12:15], v[68:71], v[188:191], v[12:15]
	v_mfma_f32_16x16x32_bf16 v[8:11], v[76:79], v[188:191], v[8:11]
	s_setprio 0
	s_setprio 1
	v_mfma_f32_16x16x32_bf16 v[52:55], v[144:147], v[160:163], v[52:55]
	v_mfma_f32_16x16x32_bf16 v[48:51], v[152:155], v[160:163], v[48:51]
	v_mfma_f32_16x16x32_bf16 v[36:39], v[144:147], v[168:171], v[36:39]
	v_mfma_f32_16x16x32_bf16 v[32:35], v[152:155], v[168:171], v[32:35]
	v_mfma_f32_16x16x32_bf16 v[20:23], v[144:147], v[176:179], v[20:23]
	v_mfma_f32_16x16x32_bf16 v[16:19], v[152:155], v[176:179], v[16:19]
	v_mfma_f32_16x16x32_bf16 v[4:7], v[144:147], v[184:187], v[4:7]
	v_mfma_f32_16x16x32_bf16 v[0:3], v[152:155], v[184:187], v[0:3]
	v_mfma_f32_16x16x32_bf16 v[52:55], v[148:151], v[164:167], v[52:55]
	v_mfma_f32_16x16x32_bf16 v[48:51], v[156:159], v[164:167], v[48:51]
	v_mfma_f32_16x16x32_bf16 v[36:39], v[148:151], v[172:175], v[36:39]
	v_mfma_f32_16x16x32_bf16 v[32:35], v[156:159], v[172:175], v[32:35]
	v_mfma_f32_16x16x32_bf16 v[20:23], v[148:151], v[180:183], v[20:23]
	v_mfma_f32_16x16x32_bf16 v[16:19], v[156:159], v[180:183], v[16:19]
	v_mfma_f32_16x16x32_bf16 v[4:7], v[148:151], v[188:191], v[4:7]
	v_mfma_f32_16x16x32_bf16 v[0:3], v[156:159], v[188:191], v[0:3]
	s_barrier
	s_setprio 0
	s_add_i32 s72, 0, 0x18000
	s_add_i32 s74, 0, 0x1c000
	v_add_u32_e32 v76, s72, v244
	v_add_u32_e32 v156, s74, v244
	ds_read_b128 v[64:67], v76
	ds_read_b128 v[68:71], v76 offset:1024
	ds_read_b128 v[72:75], v76 offset:2048
	ds_read_b128 v[76:79], v76 offset:3072
	ds_read_b128 v[144:147], v156
	ds_read_b128 v[148:151], v156 offset:1024
	ds_read_b128 v[152:155], v156 offset:2048
	ds_read_b128 v[156:159], v156 offset:3072
	s_add_u32 s34, s68, 0x200000
	s_addc_u32 s35, s69, 0
	s_mov_b32 m0, s83
	v_lshl_add_u64 v[200:201], s[34:35], 0, v[214:215]
	ds_read_b128 v[160:163], v245 offset:32768
	ds_read_b128 v[164:167], v245 offset:33792
	ds_read_b128 v[168:171], v245 offset:34816
	ds_read_b128 v[172:175], v245 offset:35840
	ds_read_b128 v[176:179], v245 offset:36864
	ds_read_b128 v[180:183], v245 offset:37888
	ds_read_b128 v[184:187], v245 offset:38912
	ds_read_b128 v[188:191], v245 offset:39936
	global_load_lds_dwordx4 v[200:201], off
	v_lshl_add_u64 v[200:201], s[34:35], 0, v[212:213]
	s_mov_b32 m0, s84
	s_nop 0
	global_load_lds_dwordx4 v[200:201], off
	s_waitcnt vmcnt(8)
	s_waitcnt lgkmcnt(0)
	s_setprio 1
	s_barrier
	s_waitcnt lgkmcnt(0)
	v_mfma_f32_16x16x32_bf16 v[140:143], v[64:67], v[160:163], v[140:143]
	v_mfma_f32_16x16x32_bf16 v[136:139], v[72:75], v[160:163], v[136:139]
	v_mfma_f32_16x16x32_bf16 v[124:127], v[64:67], v[168:171], v[124:127]
	v_mfma_f32_16x16x32_bf16 v[120:123], v[72:75], v[168:171], v[120:123]
	v_mfma_f32_16x16x32_bf16 v[108:111], v[64:67], v[176:179], v[108:111]
	v_mfma_f32_16x16x32_bf16 v[104:107], v[72:75], v[176:179], v[104:107]
	v_mfma_f32_16x16x32_bf16 v[92:95], v[64:67], v[184:187], v[92:95]
	v_mfma_f32_16x16x32_bf16 v[88:91], v[72:75], v[184:187], v[88:91]
	v_mfma_f32_16x16x32_bf16 v[140:143], v[68:71], v[164:167], v[140:143]
	v_mfma_f32_16x16x32_bf16 v[136:139], v[76:79], v[164:167], v[136:139]
	v_mfma_f32_16x16x32_bf16 v[124:127], v[68:71], v[172:175], v[124:127]
	v_mfma_f32_16x16x32_bf16 v[120:123], v[76:79], v[172:175], v[120:123]
	v_mfma_f32_16x16x32_bf16 v[108:111], v[68:71], v[180:183], v[108:111]
	v_mfma_f32_16x16x32_bf16 v[104:107], v[76:79], v[180:183], v[104:107]
	v_mfma_f32_16x16x32_bf16 v[92:95], v[68:71], v[188:191], v[92:95]
	v_mfma_f32_16x16x32_bf16 v[88:91], v[76:79], v[188:191], v[88:91]
	s_setprio 0
	s_setprio 1
	v_mfma_f32_16x16x32_bf16 v[132:135], v[144:147], v[160:163], v[132:135]
	v_mfma_f32_16x16x32_bf16 v[128:131], v[152:155], v[160:163], v[128:131]
	v_mfma_f32_16x16x32_bf16 v[116:119], v[144:147], v[168:171], v[116:119]
	v_mfma_f32_16x16x32_bf16 v[112:115], v[152:155], v[168:171], v[112:115]
	v_mfma_f32_16x16x32_bf16 v[100:103], v[144:147], v[176:179], v[100:103]
	v_mfma_f32_16x16x32_bf16 v[96:99], v[152:155], v[176:179], v[96:99]
	v_mfma_f32_16x16x32_bf16 v[84:87], v[144:147], v[184:187], v[84:87]
	v_mfma_f32_16x16x32_bf16 v[80:83], v[152:155], v[184:187], v[80:83]
	v_mfma_f32_16x16x32_bf16 v[132:135], v[148:151], v[164:167], v[132:135]
	v_mfma_f32_16x16x32_bf16 v[128:131], v[156:159], v[164:167], v[128:131]
	v_mfma_f32_16x16x32_bf16 v[116:119], v[148:151], v[172:175], v[116:119]
	v_mfma_f32_16x16x32_bf16 v[112:115], v[156:159], v[172:175], v[112:115]
	v_mfma_f32_16x16x32_bf16 v[100:103], v[148:151], v[180:183], v[100:103]
	v_mfma_f32_16x16x32_bf16 v[96:99], v[156:159], v[180:183], v[96:99]
	v_mfma_f32_16x16x32_bf16 v[84:87], v[148:151], v[188:191], v[84:87]
	v_mfma_f32_16x16x32_bf16 v[80:83], v[156:159], v[188:191], v[80:83]
	s_barrier
; #define PG8_STAGE(bufoff, gbase, voff) do { _Pragma("unroll") for (int _i = 0; _i < 2; ++_i) \
;         __builtin_amdgcn_global_load_lds((const unsigned*)((const char*)(gbase) + (voff)[_i]), (PG8_LAS unsigned*)(lds + (bufoff) + ldsw + _i * 8192), 16, 0, 0); } while (0)
; #define PG8_LDA(dst, b, h) do { _Pragma("unroll") for (int m = 0; m < 4; ++m) _Pragma("unroll") for (int k = 0; k < 2; ++k) dst[m][k] = *(const PG8_LAS bf16x8*)(lds + PG8_SA(b, h) + aoff + m * 2048 + k * 1024); } while (0)
; #define PG8_MMA(ai, bj, At, Bt) do { __builtin_amdgcn_s_setprio(1); _Pragma("unroll") for (int m = 0; m < 4; ++m) _Pragma("unroll") for (int n = 0; n < 2; ++n) _Pragma("unroll") for (int k = 0; k < 2; ++k) \
;         acc[ai][bj][m][n] = __builtin_amdgcn_mfma_f32_16x16x32_bf16(Bt[n][k], At[m][k], acc[ai][bj][m][n], 0, 0, 0); __builtin_amdgcn_s_setprio(0); } while (0)
; #define PG8_WAIT_V(n) asm volatile("s_waitcnt vmcnt(" #n ")" ::: "memory")
; #define PG8_WAIT_L(n) asm volatile("s_waitcnt lgkmcnt(" #n ")" ::: "memory")
; #define PG8_BAR __builtin_amdgcn_s_barrier()
; #define PG8_SCHED __builtin_amdgcn_sched_barrier(0)
; template <class Epi, class Sched, bool ALIGN_EPI = false, bool SP2 = false>
; __device__ __forceinline__ void gemm_phase(PG8_LAS unsigned char* lds, const Gemm g, const Sched& S, const Epi& E) {
;     ...
;             PG8_LDA(At, 1, 1); PG8_STAGE(PG8_SB(1, 0), b3, voffB); PG8_STAGE(PG8_SB(1, 1), b3 + hstep, voffB); PG8_STAGE(PG8_SA(1, 0), a3, voffA);
;             PG8_WAIT_V(8); PG8_WAIT_L(0); PG8_BAR; PG8_MMA(1, 0, At, B0); PG8_MMA(1, 1, At, B1); PG8_BAR; PG8_SCHED;
;     ...
;         if constexpr (ALIGN_EPI) { if (wr == 0) PG8_BAR; }
	s_setprio 0
	s_add_i32 s34, s72, s80
	v_lshl_add_u64 v[192:193], v[192:193], 0, s[8:9]
	s_mov_b32 m0, s34
	ds_read_b128 v[160:163], v245 offset:49152
	ds_read_b128 v[164:167], v245 offset:50176
	ds_read_b128 v[168:171], v245 offset:51200
	ds_read_b128 v[172:175], v245 offset:52224
	ds_read_b128 v[176:179], v245 offset:53248
	ds_read_b128 v[180:183], v245 offset:54272
	ds_read_b128 v[184:187], v245 offset:55296
	ds_read_b128 v[188:191], v245 offset:56320
	global_load_lds_dwordx4 v[192:193], off
	s_add_i32 m0, s34, 0x2000
	s_add_u32 s34, s66, 0x200080
	v_lshl_add_u64 v[192:193], v[194:195], 0, s[8:9]
	s_addc_u32 s35, s67, 0
	s_add_i32 s66, s74, s80
	global_load_lds_dwordx4 v[192:193], off
	v_lshl_add_u64 v[192:193], s[34:35], 0, v[204:205]
	s_mov_b32 m0, s66
	s_nop 0
	global_load_lds_dwordx4 v[192:193], off
	v_lshl_add_u64 v[192:193], s[34:35], 0, v[210:211]
	s_add_i32 m0, s66, 0x2000
	s_nop 0
	global_load_lds_dwordx4 v[192:193], off
	v_lshl_add_u64 v[192:193], v[196:197], 0, s[8:9]
	s_mov_b32 m0, s87
	s_nop 0
	global_load_lds_dwordx4 v[192:193], off
	v_lshl_add_u64 v[192:193], v[198:199], 0, s[8:9]
	s_mov_b32 m0, s88
	s_nop 0
	global_load_lds_dwordx4 v[192:193], off
	s_waitcnt vmcnt(8)
	s_waitcnt lgkmcnt(0)
	s_setprio 1
	s_barrier
	s_waitcnt lgkmcnt(0)
	v_mfma_f32_16x16x32_bf16 v[60:63], v[64:67], v[160:163], v[60:63]
	v_mfma_f32_16x16x32_bf16 v[56:59], v[72:75], v[160:163], v[56:59]
	v_mfma_f32_16x16x32_bf16 v[44:47], v[64:67], v[168:171], v[44:47]
	v_mfma_f32_16x16x32_bf16 v[40:43], v[72:75], v[168:171], v[40:43]
	v_mfma_f32_16x16x32_bf16 v[28:31], v[64:67], v[176:179], v[28:31]
	v_mfma_f32_16x16x32_bf16 v[24:27], v[72:75], v[176:179], v[24:27]
	v_mfma_f32_16x16x32_bf16 v[12:15], v[64:67], v[184:187], v[12:15]
	v_mfma_f32_16x16x32_bf16 v[8:11], v[72:75], v[184:187], v[8:11]
	v_mfma_f32_16x16x32_bf16 v[60:63], v[68:71], v[164:167], v[60:63]
	v_mfma_f32_16x16x32_bf16 v[56:59], v[76:79], v[164:167], v[56:59]
	v_mfma_f32_16x16x32_bf16 v[44:47], v[68:71], v[172:175], v[44:47]
	v_mfma_f32_16x16x32_bf16 v[40:43], v[76:79], v[172:175], v[40:43]
	v_mfma_f32_16x16x32_bf16 v[28:31], v[68:71], v[180:183], v[28:31]
	v_mfma_f32_16x16x32_bf16 v[24:27], v[76:79], v[180:183], v[24:27]
	v_mfma_f32_16x16x32_bf16 v[12:15], v[68:71], v[188:191], v[12:15]
	v_mfma_f32_16x16x32_bf16 v[8:11], v[76:79], v[188:191], v[8:11]
	s_setprio 0
	s_setprio 1
	v_mfma_f32_16x16x32_bf16 v[52:55], v[144:147], v[160:163], v[52:55]
	v_mfma_f32_16x16x32_bf16 v[48:51], v[152:155], v[160:163], v[48:51]
	v_mfma_f32_16x16x32_bf16 v[36:39], v[144:147], v[168:171], v[36:39]
	v_mfma_f32_16x16x32_bf16 v[32:35], v[152:155], v[168:171], v[32:35]
	v_mfma_f32_16x16x32_bf16 v[20:23], v[144:147], v[176:179], v[20:23]
	v_mfma_f32_16x16x32_bf16 v[16:19], v[152:155], v[176:179], v[16:19]
	v_mfma_f32_16x16x32_bf16 v[4:7], v[144:147], v[184:187], v[4:7]
	v_mfma_f32_16x16x32_bf16 v[0:3], v[152:155], v[184:187], v[0:3]
	v_mfma_f32_16x16x32_bf16 v[52:55], v[148:151], v[164:167], v[52:55]
	v_mfma_f32_16x16x32_bf16 v[48:51], v[156:159], v[164:167], v[48:51]
	v_mfma_f32_16x16x32_bf16 v[36:39], v[148:151], v[172:175], v[36:39]
	v_mfma_f32_16x16x32_bf16 v[32:35], v[156:159], v[172:175], v[32:35]
	v_mfma_f32_16x16x32_bf16 v[20:23], v[148:151], v[180:183], v[20:23]
	v_mfma_f32_16x16x32_bf16 v[16:19], v[156:159], v[180:183], v[16:19]
	v_mfma_f32_16x16x32_bf16 v[4:7], v[148:151], v[188:191], v[4:7]
	v_mfma_f32_16x16x32_bf16 v[0:3], v[156:159], v[188:191], v[0:3]
	s_barrier
	s_setprio 0
	s_add_i32 vcc_hi, vcc_hi, 2
	s_add_u32 s4, s4, 0x100
	s_addc_u32 s5, s5, 0
	s_add_u32 s99, s99, 0x100
	s_addc_u32 vcc_lo, vcc_lo, 0
	s_cmpk_gt_u32 vcc_hi, 0x7d
	s_cbranch_scc0 .LBB0_493
	s_and_b64 vcc, exec, s[10:11]
	s_cbranch_vccz .LBB0_496
	s_barrier
